# norm phases: per-wave rotation of column quarters (slot j of wave w handles block (j+w)&3) to spread XN store / x load memory channels; on top of v23
# baseline (speedup 1.0000x reference)
; __device__ __forceinline__ void norm_mod_phase(const float* x, const float* x0src, size_t x0stride, float* h0buf, const float* g, const float* sh, const float* sc, bf16* XN, int gw, int NGW, int lane) {
;     const int wpb = NGW / BATCH, rpw = T / wpb;
;     const int b = gw / wpb, wi = gw - b * wpb;
;     f32x4 gm[4], s0[4];
; #pragma unroll
;     for (int j = 0; j < 4; ++j) { const int col = 4 * lane + 256 * j; gm[j] = *(const f32x4*)(g + col) * (*(const f32x4*)(sc + b * NMOD + col) + 1.f); s0[j] = *(const f32x4*)(sh + b * NMOD + col); }
;     for (int k = 0; k < rpw; k += 4) {
.LBB0_161:
	s_abs_i32 s18, s19
	v_cvt_f32_u32_e32 v1, s18
	v_readlane_b32 s5, v255, 2
	s_ashr_i32 s20, s19, 31
	v_rcp_iflag_f32_e32 v1, v1
	v_mov_b32_e32 v2, s5
	s_sub_i32 s5, 0, s18
	ds_read_b64 v[2:3], v2
	v_mul_f32_e32 v1, 0x4f7ffffe, v1
	v_cvt_u32_f32_e32 v1, v1
	s_waitcnt lgkmcnt(0)
	v_readfirstlane_b32 s64, v2
	v_readfirstlane_b32 s65, v1
	s_mul_i32 s5, s5, s65
	s_mul_hi_u32 s5, s65, s5
	s_add_i32 s65, s65, s5
	s_lshr_b32 s5, s65, 20
	s_mul_i32 s8, s5, s18
	s_sub_i32 s8, 0x1000, s8
	s_add_i32 s9, s5, 1
	s_sub_i32 s12, s8, s18
	s_cmp_ge_u32 s8, s18
	s_cselect_b32 s5, s9, s5
	s_cselect_b32 s8, s12, s8
	s_add_i32 s9, s5, 1
	s_cmp_ge_u32 s8, s18
	s_cselect_b32 s5, s9, s5
	s_xor_b32 s5, s5, s20
	s_sub_i32 s8, s5, s20
	s_cmp_lt_i32 s8, 1
	v_readfirstlane_b32 s66, v3
	s_cbranch_scc1 .LBB0_196
	s_mul_i32 s12, s62, 0xc000
	s_ashr_i32 s5, s7, 6
	s_lshl_b32 s9, s6, 3
	s_lshl_b32 s68, s62, 10
	s_add_i32 s67, s5, s9
	s_lshl_b64 s[6:7], s[12:13], 2
	s_mov_b32 s69, s13
	s_add_u32 s12, s61, s6
	s_addc_u32 s70, s63, s7
	s_lshl_b64 s[6:7], s[68:69], 2
	s_add_u32 s68, s64, s6
	s_addc_u32 s69, s66, s7
	s_ashr_i32 s6, s67, 31
	s_xor_b32 s64, s6, s20
	s_abs_i32 s6, s67
	s_mul_hi_u32 s7, s6, s65
	s_mul_i32 s20, s7, s18
	s_sub_i32 s6, s6, s20
	s_add_i32 s20, s7, 1
	s_sub_i32 s65, s6, s18
	s_cmp_ge_u32 s6, s18
	s_cselect_b32 s7, s20, s7
	s_cselect_b32 s6, s65, s6
	s_add_i32 s20, s7, 1
	s_cmp_ge_u32 s6, s18
	s_cselect_b32 s6, s20, s7
	s_xor_b32 s65, s6, s64
	s_sub_i32 s6, s65, s64
	s_mul_i32 s66, s6, 0x1800
	s_ashr_i32 s67, s66, 31
	s_lshl_b64 s[66:67], s[66:67], 2
	v_and_b32_e32 v16, 63, v0
	s_add_u32 s66, s12, s66
	s_addc_u32 s67, s70, s67
	v_lshlrev_b32_e32 v162, 4, v16
	v_lshl_add_u64 v[0:1], s[66:67], 0, v[162:163]
	v_readfirstlane_b32 s98, v160
	s_nop 3
	s_lshr_b32 s98, s98, 6
	v_and_b32_e32 v136, 63, v160
	v_lshlrev_b32_e32 v136, 4, v136
	s_add_i32 s99, s98, 0
	s_and_b32 s99, s99, 3
	s_lshl_b32 s99, s99, 10
	v_add_u32_e32 v116, s99, v136
	v_mov_b32_e32 v120, s99
	v_mov_b32_e32 v121, 0
	s_lshr_b32 s99, s99, 1
	v_mov_b32_e32 v128, s99
	v_mov_b32_e32 v129, 0
	s_add_i32 s99, s98, 1
	s_and_b32 s99, s99, 3
	s_lshl_b32 s99, s99, 10
	v_add_u32_e32 v117, s99, v136
	v_mov_b32_e32 v122, s99
	v_mov_b32_e32 v123, 0
	s_lshr_b32 s99, s99, 1
	v_mov_b32_e32 v130, s99
	v_mov_b32_e32 v131, 0
	s_add_i32 s99, s98, 2
	s_and_b32 s99, s99, 3
	s_lshl_b32 s99, s99, 10
	v_add_u32_e32 v118, s99, v136
	v_mov_b32_e32 v124, s99
	v_mov_b32_e32 v125, 0
	s_lshr_b32 s99, s99, 1
	v_mov_b32_e32 v132, s99
	v_mov_b32_e32 v133, 0
	s_add_i32 s99, s98, 3
	s_and_b32 s99, s99, 3
	s_lshl_b32 s99, s99, 10
	v_add_u32_e32 v119, s99, v136
	v_mov_b32_e32 v126, s99
	v_mov_b32_e32 v127, 0
	s_lshr_b32 s99, s99, 1
	v_mov_b32_e32 v134, s99
	v_mov_b32_e32 v135, 0
	v_add_co_u32_e32 v2, vcc, s46, v0
	s_mov_b64 s[34:35], 0x1000
	s_nop 0
	v_addc_co_u32_e32 v3, vcc, 0, v1, vcc
	v_lshl_add_u64 v[136:137], v[2:3], 0, v[120:121]
	global_load_dwordx4 v[18:21], v[136:137], off
	v_lshl_add_u64 v[0:1], v[0:1], 0, s[34:35]
	v_lshl_add_u64 v[136:137], v[0:1], 0, v[122:123]
	global_load_dwordx4 v[22:25], v[136:137], off
	v_lshl_add_u64 v[136:137], v[0:1], 0, v[124:125]
	global_load_dwordx4 v[26:29], v[136:137], off
	v_lshl_add_u64 v[136:137], v[0:1], 0, v[126:127]
	global_load_dwordx4 v[30:33], v[136:137], off
	global_load_dwordx4 v[34:37], v116, s[68:69]
	global_load_dwordx4 v[38:41], v117, s[68:69]
	global_load_dwordx4 v[42:45], v118, s[68:69]
	global_load_dwordx4 v[46:49], v119, s[68:69]
	s_nop 0
	global_load_dwordx4 v[0:3], v116, s[66:67]
	global_load_dwordx4 v[4:7], v117, s[66:67]
	global_load_dwordx4 v[8:11], v118, s[66:67]
	global_load_dwordx4 v[12:15], v119, s[66:67]
	s_ashr_i32 s7, s6, 31
	s_lshl_b64 s[68:69], s[6:7], 24
	s_mul_hi_i32 s67, s4, s6
	s_mul_i32 s66, s4, s6
	s_add_u32 s16, s16, s68
	s_addc_u32 s17, s17, s69
	s_lshl_b64 s[66:67], s[66:67], 2
	s_add_u32 s18, s0, s66
	s_addc_u32 s20, s1, s67
	s_lshl_b64 s[0:1], s[6:7], 23
	s_add_u32 s0, s61, s0
	s_mul_i32 s70, s6, s19
	s_addc_u32 s1, s63, s1
	s_lshl_b32 s6, s6, 10
	s_ashr_i32 s7, s6, 31
	s_lshl_b64 s[6:7], s[6:7], 2
	s_add_u32 s6, s61, s6
	s_addc_u32 s7, s63, s7
	v_cmp_lt_i32_e32 vcc, v228, v222
	v_xor_b32_e32 v50, 2, v221
	s_lshl_b32 s63, s19, 2
	v_cndmask_b32_e32 v17, v221, v228, vcc
	v_cmp_lt_i32_e32 vcc, v50, v222
	s_mov_b32 s12, 0
	v_lshlrev_b32_e32 v104, 2, v17
	v_cndmask_b32_e32 v50, v221, v50, vcc
	v_cmp_lt_i32_e32 vcc, v218, v222
	v_lshlrev_b32_e32 v105, 2, v50
	s_sub_i32 s78, s5, s70
	v_cndmask_b32_e32 v51, v221, v218, vcc
	v_cmp_lt_i32_e32 vcc, v219, v222
	v_lshlrev_b32_e32 v106, 2, v51
	v_lshlrev_b32_e32 v110, 4, v16
	v_cndmask_b32_e32 v52, v221, v219, vcc
	v_cmp_lt_i32_e32 vcc, v254, v222
	v_lshlrev_b32_e32 v107, 2, v52
	s_waitcnt vmcnt(0)
	v_pk_add_f32 v[24:25], v[24:25], 1.0 op_sel_hi:[1,0]
	v_cndmask_b32_e32 v53, v221, v254, vcc
	v_cmp_lt_i32_e32 vcc, v223, v222
	v_pk_add_f32 v[22:23], v[22:23], 1.0 op_sel_hi:[1,0]
	s_waitcnt vmcnt(9)
	v_pk_add_f32 v[28:29], v[28:29], 1.0 op_sel_hi:[1,0]
	v_cndmask_b32_e32 v54, v221, v223, vcc
	v_pk_add_f32 v[26:27], v[26:27], 1.0 op_sel_hi:[1,0]
	s_waitcnt vmcnt(8)
	v_pk_add_f32 v[32:33], v[32:33], 1.0 op_sel_hi:[1,0]
	v_pk_add_f32 v[18:19], v[18:19], 1.0 op_sel_hi:[1,0]
	v_pk_add_f32 v[20:21], v[20:21], 1.0 op_sel_hi:[1,0]
	s_waitcnt vmcnt(7)
	v_pk_mul_f32 v[82:83], v[34:35], v[18:19]
	v_lshl_add_u64 v[18:19], s[6:7], 0, v[162:163]
	s_mov_b64 s[6:7], 0x598000
	v_lshlrev_b32_e32 v162, 3, v16
	v_lshl_add_u64 v[96:97], v[18:19], 0, s[6:7]
	v_lshl_add_u64 v[18:19], s[0:1], 0, v[162:163]
	s_mov_b64 s[0:1], 0x6e00000
	v_lshl_add_u64 v[98:99], v[18:19], 0, s[0:1]
	s_sub_i32 s0, s64, s65
	s_add_i32 s1, s0, 1
	s_mul_i32 s1, s19, s1
	s_add_i32 s61, s5, s1
	s_add_i32 s1, s0, 2
	s_add_i32 s0, s0, 3
	v_pk_add_f32 v[30:31], v[30:31], 1.0 op_sel_hi:[1,0]
	s_mul_i32 s1, s19, s1
	s_mul_i32 s19, s19, s0
	v_lshlrev_b32_e32 v108, 2, v53
	v_lshlrev_b32_e32 v109, 2, v54
	v_pk_mul_f32 v[80:81], v[36:37], v[20:21]
	s_waitcnt vmcnt(6)
	v_pk_mul_f32 v[84:85], v[40:41], v[24:25]
	v_pk_mul_f32 v[86:87], v[38:39], v[22:23]
	s_waitcnt vmcnt(5)
	v_pk_mul_f32 v[88:89], v[44:45], v[28:29]
	v_pk_mul_f32 v[90:91], v[42:43], v[26:27]
	s_waitcnt vmcnt(4)
	v_pk_mul_f32 v[92:93], v[48:49], v[32:33]
	v_pk_mul_f32 v[94:95], v[46:47], v[30:31]
	s_add_i32 s76, s5, s1
	s_add_i32 s77, s5, s19
	s_branch .LBB0_164

; __device__ __forceinline__ unsigned pk2(float lo, float hi) { return f2bf(lo) | (f2bf(hi) << 16); }
; __device__ __forceinline__ void norm_mod_phase(const float* x, const float* x0src, size_t x0stride, float* h0buf, const float* g, const float* sh, const float* sc, bf16* XN, int gw, int NGW, int lane) {
;     ...
;     for (int k = 0; k < rpw; k += 4) {
;         f32x4 v[4][4];
; #pragma unroll
;         for (int r = 0; r < 4; ++r) { const int t = wi + wpb * (k + r); const bool t0 = t == 0;
;             const f32x4* xr = (const f32x4*)(t0 ? x0src + (size_t)b * x0stride : x + ((size_t)b * T + t) * D) + lane;
; #pragma unroll
;             for (int j = 0; j < 4; ++j) v[r][j] = xr[64 * j]; }
;         __builtin_amdgcn_sched_barrier(0);
; #pragma unroll
;         for (int r = 0; r < 4; ++r) { const int t = wi + wpb * (k + r); const bool t0 = t == 0; const size_t row = (size_t)b * T + t;
;             float ss = 0.f;
; #pragma unroll
;             for (int j = 0; j < 4; ++j) ss += (v[r][j].x * v[r][j].x + v[r][j].y * v[r][j].y) + (v[r][j].z * v[r][j].z + v[r][j].w * v[r][j].w);
;             const float rstd = 1.f / sqrtf(wave_sum(ss) * (1.f / D) + EPS);
; #pragma unroll
;             for (int j = 0; j < 4; ++j) { const int col = 4 * lane + 256 * j;
;                 const f32x4 h = v[r][j] * rstd * gm[j] + s0[j];
;                 v2u o; o.x = pk2(h.x, h.y); o.y = pk2(h.z, h.w);
;                 *(v2u*)(XN + row * D + col) = o;
;                 if (t0) *(f32x4*)(h0buf + b * D + col) = h; } }
.LBB0_164:
	s_add_i32 s0, s9, s78
	s_ashr_i32 s1, s0, 31
	s_lshl_b64 s[4:5], s[0:1], 12
	s_add_u32 s6, s16, s4
	s_addc_u32 s7, s17, s5
	s_cmp_eq_u32 s0, 0
	s_cselect_b64 s[72:73], -1, 0
	s_and_b64 s[4:5], s[72:73], exec
	s_cselect_b32 s74, s18, s6
	s_cselect_b32 s75, s20, s7
	s_add_i32 s70, s9, s61
	s_ashr_i32 s71, s70, 31
	s_lshl_b64 s[4:5], s[70:71], 12
	s_add_u32 s6, s16, s4
	s_addc_u32 s7, s17, s5
	s_cmp_eq_u32 s70, 0
	s_cselect_b64 s[68:69], -1, 0
	s_and_b64 s[4:5], s[68:69], exec
	s_cselect_b32 s80, s18, s6
	s_cselect_b32 s81, s20, s7
	s_add_i32 s66, s9, s76
	s_ashr_i32 s67, s66, 31
	s_lshl_b64 s[4:5], s[66:67], 12
	s_add_u32 s6, s16, s4
	s_addc_u32 s7, s17, s5
	s_cmp_eq_u32 s66, 0
	s_cselect_b64 s[64:65], -1, 0
	s_and_b64 s[4:5], s[64:65], exec
	s_cselect_b32 s82, s18, s6
	s_cselect_b32 s83, s20, s7
	s_add_i32 s6, s9, s77
	s_ashr_i32 s7, s6, 31
	s_lshl_b64 s[4:5], s[6:7], 12
	s_add_u32 s19, s16, s4
	s_addc_u32 s79, s17, s5
	s_cmp_eq_u32 s6, 0
	s_cselect_b64 s[4:5], -1, 0
	s_and_b64 s[84:85], s[4:5], exec
	s_cselect_b32 s84, s18, s19
	s_cselect_b32 s85, s20, s79
	global_load_dwordx4 v[76:79], v116, s[74:75]
	global_load_dwordx4 v[72:75], v117, s[74:75]
	global_load_dwordx4 v[68:71], v118, s[74:75]
	global_load_dwordx4 v[64:67], v119, s[74:75]
	global_load_dwordx4 v[60:63], v116, s[80:81]
	global_load_dwordx4 v[56:59], v117, s[80:81]
	global_load_dwordx4 v[52:55], v118, s[80:81]
	global_load_dwordx4 v[48:51], v119, s[80:81]
	global_load_dwordx4 v[44:47], v116, s[82:83]
	global_load_dwordx4 v[40:43], v117, s[82:83]
	global_load_dwordx4 v[36:39], v118, s[82:83]
	global_load_dwordx4 v[32:35], v119, s[82:83]
	global_load_dwordx4 v[28:31], v116, s[84:85]
	global_load_dwordx4 v[24:27], v117, s[84:85]
	global_load_dwordx4 v[20:23], v118, s[84:85]
	global_load_dwordx4 v[16:19], v119, s[84:85]
	s_lshl_b64 s[74:75], s[0:1], 11
	s_cmp_lg_u32 s0, 0
	s_waitcnt vmcnt(15)
	v_pk_mul_f32 v[100:101], v[78:79], v[78:79]
	v_pk_mul_f32 v[102:103], v[76:77], v[76:77]
	s_waitcnt vmcnt(12)
	v_mul_f32_e32 v111, v64, v64
	v_pk_mov_b32 v[112:113], v[102:103], v[100:101] op_sel:[1,0]
	v_mov_b32_e32 v103, v101
	v_pk_add_f32 v[100:101], v[112:113], v[102:103]
	v_pk_mul_f32 v[102:103], v[74:75], v[74:75]
	v_pk_mul_f32 v[112:113], v[72:73], v[72:73]
	v_pk_add_f32 v[100:101], v[100:101], v[100:101] op_sel:[0,1] op_sel_hi:[1,0]
	v_pk_mov_b32 v[114:115], v[112:113], v[102:103] op_sel:[1,0]
	v_mov_b32_e32 v113, v103
	v_pk_add_f32 v[102:103], v[114:115], v[112:113]
	v_mul_f32_e32 v112, v65, v65
	v_pk_add_f32 v[102:103], v[102:103], v[102:103] op_sel:[0,1] op_sel_hi:[1,0]
	v_mov_b32_e32 v101, v111
	v_mov_b32_e32 v103, v112
	v_pk_add_f32 v[100:101], v[100:101], v[102:103]
	v_mul_f32_e32 v102, v69, v69
	v_mul_f32_e32 v113, v66, v66
	v_pk_fma_f32 v[102:103], v[68:69], v[68:69], v[102:103] op_sel_hi:[1,1,0]
	v_mul_f32_e32 v112, v71, v71
	v_mul_f32_e32 v114, v67, v67
	v_mov_b32_e32 v103, v113
	v_pk_fma_f32 v[112:113], v[70:71], v[70:71], v[112:113] op_sel_hi:[1,1,0]
	s_nop 0
	v_mov_b32_e32 v113, v114
	v_pk_add_f32 v[102:103], v[102:103], v[112:113]
	s_nop 0
	v_pk_add_f32 v[100:101], v[100:101], v[102:103]
	s_nop 0
	v_add_f32_e32 v100, v100, v101
	ds_bpermute_b32 v101, v104, v100
	s_waitcnt lgkmcnt(0)
	v_add_f32_e32 v100, v100, v101
	ds_bpermute_b32 v101, v105, v100
	s_waitcnt lgkmcnt(0)
	v_add_f32_e32 v100, v100, v101
	ds_bpermute_b32 v101, v106, v100
	s_waitcnt lgkmcnt(0)
	v_add_f32_e32 v100, v100, v101
	ds_bpermute_b32 v101, v107, v100
	s_waitcnt lgkmcnt(0)
	v_add_f32_e32 v100, v100, v101
	ds_bpermute_b32 v101, v108, v100
	s_waitcnt lgkmcnt(0)
	v_add_f32_e32 v100, v100, v101
	ds_bpermute_b32 v101, v109, v100
	s_waitcnt lgkmcnt(0)
	v_add_f32_e32 v100, v100, v101
	v_fmamk_f32 v100, v100, 0x3a800000, v161
	v_mul_f32_e32 v101, 0x4f800000, v100
	v_cmp_gt_f32_e32 vcc, s58, v100
	s_nop 1
	v_cndmask_b32_e32 v100, v100, v101, vcc
	v_sqrt_f32_e32 v101, v100
	s_nop 0
	v_add_u32_e32 v102, -1, v101
	v_add_u32_e32 v103, 1, v101
	v_fma_f32 v111, -v102, v101, v100
	v_fma_f32 v112, -v103, v101, v100
	v_cmp_ge_f32_e64 s[0:1], 0, v111
	s_nop 1
	v_cndmask_b32_e64 v101, v101, v102, s[0:1]
	v_cmp_lt_f32_e64 s[0:1], 0, v112
	s_nop 1
	v_cndmask_b32_e64 v101, v101, v103, s[0:1]
	v_mul_f32_e32 v102, 0x37800000, v101
	v_cndmask_b32_e32 v101, v101, v102, vcc
	v_cmp_class_f32_e32 vcc, v100, v177
	s_nop 1
	v_cndmask_b32_e32 v100, v101, v100, vcc
	v_div_scale_f32 v101, s[0:1], v100, v100, 1.0
	v_rcp_f32_e32 v102, v101
	v_div_scale_f32 v103, vcc, 1.0, v100, 1.0
	v_fma_f32 v111, -v101, v102, 1.0
	v_fmac_f32_e32 v102, v111, v102
	v_mul_f32_e32 v111, v103, v102
	v_fma_f32 v112, -v101, v111, v103
	v_fmac_f32_e32 v111, v112, v102
	v_fma_f32 v101, -v101, v111, v103
	v_div_fmas_f32 v101, v101, v102, v111
	v_div_fixup_f32 v100, v101, v100, 1.0
	v_pk_mul_f32 v[76:77], v[76:77], v[100:101] op_sel_hi:[1,0]
	v_pk_mul_f32 v[78:79], v[78:79], v[100:101] op_sel_hi:[1,0]
	v_pk_fma_f32 v[76:77], v[82:83], v[76:77], v[0:1]
	v_pk_fma_f32 v[78:79], v[80:81], v[78:79], v[2:3]
	v_bfe_u32 v101, v76, 16, 1
	v_add3_u32 v101, v76, v101, s59
	v_bfe_u32 v102, v77, 16, 1
	v_lshrrev_b32_e32 v101, 16, v101
	v_add3_u32 v102, v77, v102, s59
	v_and_or_b32 v112, v102, s60, v101
	v_bfe_u32 v101, v78, 16, 1
	v_add3_u32 v101, v78, v101, s59
	v_bfe_u32 v102, v79, 16, 1
	v_lshrrev_b32_e32 v101, 16, v101
	v_add3_u32 v102, v79, v102, s59
	v_and_or_b32 v113, v102, s60, v101
	v_lshl_add_u64 v[102:103], v[98:99], 0, s[74:75]
	v_lshl_add_u64 v[136:137], v[102:103], 0, v[128:129]
	global_store_dwordx2 v[136:137], v[112:113], off
	s_cbranch_scc1 .LBB0_166
	v_lshl_add_u64 v[136:137], v[96:97], 0, v[120:121]
	global_store_dwordx4 v[136:137], v[76:79], off
; __device__ __forceinline__ unsigned pk2(float lo, float hi) { return f2bf(lo) | (f2bf(hi) << 16); }
; __device__ __forceinline__ void norm_mod_phase(const float* x, const float* x0src, size_t x0stride, float* h0buf, const float* g, const float* sh, const float* sc, bf16* XN, int gw, int NGW, int lane) {
;     ...
;         for (int r = 0; r < 4; ++r) { const int t = wi + wpb * (k + r); const bool t0 = t == 0; const size_t row = (size_t)b * T + t;
;             float ss = 0.f;
; #pragma unroll
;             for (int j = 0; j < 4; ++j) ss += (v[r][j].x * v[r][j].x + v[r][j].y * v[r][j].y) + (v[r][j].z * v[r][j].z + v[r][j].w * v[r][j].w);
;             const float rstd = 1.f / sqrtf(wave_sum(ss) * (1.f / D) + EPS);
; #pragma unroll
;             for (int j = 0; j < 4; ++j) { const int col = 4 * lane + 256 * j;
;                 const f32x4 h = v[r][j] * rstd * gm[j] + s0[j];
;                 v2u o; o.x = pk2(h.x, h.y); o.y = pk2(h.z, h.w);
;                 *(v2u*)(XN + row * D + col) = o;
;                 if (t0) *(f32x4*)(h0buf + b * D + col) = h; } }
.LBB0_166:
	v_mov_b32_e32 v101, v100
	v_pk_mul_f32 v[72:73], v[72:73], v[100:101]
	v_mov_b32_e32 v76, v100
	v_pk_fma_f32 v[72:73], v[86:87], v[72:73], v[4:5]
	v_mov_b32_e32 v77, v100
	v_bfe_u32 v78, v72, 16, 1
	v_pk_mul_f32 v[74:75], v[74:75], v[76:77]
	v_add3_u32 v78, v72, v78, s59
	v_bfe_u32 v79, v73, 16, 1
	v_pk_fma_f32 v[74:75], v[84:85], v[74:75], v[6:7]
	v_lshrrev_b32_e32 v78, 16, v78
	v_add3_u32 v79, v73, v79, s59
	v_and_or_b32 v78, v79, s60, v78
	v_bfe_u32 v79, v74, 16, 1
	v_add3_u32 v79, v74, v79, s59
	v_bfe_u32 v111, v75, 16, 1
	v_lshrrev_b32_e32 v79, 16, v79
	v_add3_u32 v111, v75, v111, s59
	v_and_or_b32 v79, v111, s60, v79
	v_cndmask_b32_e64 v111, 0, 1, s[72:73]
	v_cmp_ne_u32_e64 s[0:1], 1, v111
	s_andn2_b64 vcc, exec, s[72:73]
	v_lshl_add_u64 v[136:137], v[102:103], 0, v[130:131]
	global_store_dwordx2 v[136:137], v[78:79], off
	s_cbranch_vccnz .LBB0_168
	v_lshl_add_u64 v[136:137], v[96:97], 0, v[122:123]
	global_store_dwordx4 v[136:137], v[72:75], off
.LBB0_168:
	v_pk_mul_f32 v[68:69], v[68:69], v[100:101]
	v_pk_mul_f32 v[70:71], v[70:71], v[76:77]
	v_pk_fma_f32 v[68:69], v[90:91], v[68:69], v[8:9]
	v_pk_fma_f32 v[70:71], v[88:89], v[70:71], v[10:11]
	v_bfe_u32 v72, v68, 16, 1
	v_add3_u32 v72, v68, v72, s59
	v_bfe_u32 v73, v69, 16, 1
	v_lshrrev_b32_e32 v72, 16, v72
	v_add3_u32 v73, v69, v73, s59
	v_and_or_b32 v72, v73, s60, v72
	v_bfe_u32 v73, v70, 16, 1
	v_add3_u32 v73, v70, v73, s59
	v_bfe_u32 v74, v71, 16, 1
	v_lshrrev_b32_e32 v73, 16, v73
	v_add3_u32 v74, v71, v74, s59
	v_and_or_b32 v73, v74, s60, v73
	s_and_b64 vcc, exec, s[0:1]
	v_lshl_add_u64 v[136:137], v[102:103], 0, v[132:133]
	global_store_dwordx2 v[136:137], v[72:73], off
	s_cbranch_vccnz .LBB0_170
	v_lshl_add_u64 v[136:137], v[96:97], 0, v[124:125]
	global_store_dwordx4 v[136:137], v[68:71], off
.LBB0_170:
	v_pk_mul_f32 v[64:65], v[64:65], v[100:101]
	s_nop 0
	v_mov_b32_e32 v68, v100
	v_mov_b32_e32 v69, v100
	v_pk_fma_f32 v[64:65], v[94:95], v[64:65], v[12:13]
	v_pk_mul_f32 v[66:67], v[66:67], v[68:69]
	v_bfe_u32 v68, v64, 16, 1
	v_add3_u32 v68, v64, v68, s59
	v_bfe_u32 v69, v65, 16, 1
	v_pk_fma_f32 v[66:67], v[92:93], v[66:67], v[14:15]
	v_lshrrev_b32_e32 v68, 16, v68
	v_add3_u32 v69, v65, v69, s59
	v_and_or_b32 v68, v69, s60, v68
	v_bfe_u32 v69, v66, 16, 1
	v_add3_u32 v69, v66, v69, s59
	v_bfe_u32 v70, v67, 16, 1
	v_lshrrev_b32_e32 v69, 16, v69
	v_add3_u32 v70, v67, v70, s59
	v_and_or_b32 v69, v70, s60, v69
	s_and_b64 vcc, exec, s[0:1]
	v_lshl_add_u64 v[136:137], v[102:103], 0, v[134:135]
	global_store_dwordx2 v[136:137], v[68:69], off
	s_cbranch_vccnz .LBB0_172
	v_lshl_add_u64 v[136:137], v[96:97], 0, v[126:127]
	global_store_dwordx4 v[136:137], v[64:67], off
.LBB0_172:
	s_waitcnt vmcnt(15)
	s_nop 0
	v_pk_mul_f32 v[64:65], v[62:63], v[62:63]
	v_pk_mul_f32 v[66:67], v[60:61], v[60:61]
	s_nop 0
	v_pk_mov_b32 v[68:69], v[66:67], v[64:65] op_sel:[1,0]
	v_mov_b32_e32 v67, v65
	v_pk_add_f32 v[64:65], v[68:69], v[66:67]
	s_waitcnt vmcnt(14)
	v_pk_mul_f32 v[66:67], v[58:59], v[58:59]
	v_pk_mul_f32 v[68:69], v[56:57], v[56:57]
	v_pk_add_f32 v[64:65], v[64:65], v[64:65] op_sel:[0,1] op_sel_hi:[1,0]
	v_pk_mov_b32 v[70:71], v[68:69], v[66:67] op_sel:[1,0]
	v_mov_b32_e32 v69, v67
	v_pk_add_f32 v[66:67], v[70:71], v[68:69]
	s_waitcnt vmcnt(12)
	v_mul_f32_e32 v68, v48, v48
	v_mul_f32_e32 v69, v49, v49
	v_pk_add_f32 v[66:67], v[66:67], v[66:67] op_sel:[0,1] op_sel_hi:[1,0]
	v_mov_b32_e32 v65, v68
	v_mov_b32_e32 v67, v69
	v_pk_add_f32 v[64:65], v[64:65], v[66:67]
	v_mul_f32_e32 v66, v53, v53
	v_mul_f32_e32 v68, v55, v55
	v_mul_f32_e32 v70, v50, v50
	v_mul_f32_e32 v71, v51, v51
	v_pk_fma_f32 v[66:67], v[52:53], v[52:53], v[66:67] op_sel_hi:[1,1,0]
	v_pk_fma_f32 v[68:69], v[54:55], v[54:55], v[68:69] op_sel_hi:[1,1,0]
	v_mov_b32_e32 v67, v70
	v_mov_b32_e32 v69, v71
	v_pk_add_f32 v[66:67], v[66:67], v[68:69]
	s_nop 0
	v_pk_add_f32 v[64:65], v[64:65], v[66:67]
	s_nop 0
	v_add_f32_e32 v64, v64, v65
	ds_bpermute_b32 v65, v104, v64
	s_waitcnt lgkmcnt(0)
	v_add_f32_e32 v64, v64, v65
	ds_bpermute_b32 v65, v105, v64
	s_waitcnt lgkmcnt(0)
	v_add_f32_e32 v64, v64, v65
	ds_bpermute_b32 v65, v106, v64
	s_waitcnt lgkmcnt(0)
	v_add_f32_e32 v64, v64, v65
	ds_bpermute_b32 v65, v107, v64
	s_waitcnt lgkmcnt(0)
	v_add_f32_e32 v64, v64, v65
	ds_bpermute_b32 v65, v108, v64
	s_waitcnt lgkmcnt(0)
	v_add_f32_e32 v64, v64, v65
	ds_bpermute_b32 v65, v109, v64
	s_waitcnt lgkmcnt(0)
	v_add_f32_e32 v64, v64, v65
	v_fmamk_f32 v64, v64, 0x3a800000, v161
	v_mul_f32_e32 v65, 0x4f800000, v64
	v_cmp_gt_f32_e32 vcc, s58, v64
	s_nop 1
	v_cndmask_b32_e32 v64, v64, v65, vcc
	v_sqrt_f32_e32 v65, v64
	s_nop 0
	v_add_u32_e32 v66, -1, v65
	v_add_u32_e32 v67, 1, v65
	v_fma_f32 v68, -v66, v65, v64
	v_fma_f32 v69, -v67, v65, v64
	v_cmp_ge_f32_e64 s[0:1], 0, v68
	s_nop 1
	v_cndmask_b32_e64 v65, v65, v66, s[0:1]
	v_cmp_lt_f32_e64 s[0:1], 0, v69
	s_nop 1
	v_cndmask_b32_e64 v65, v65, v67, s[0:1]
	v_mul_f32_e32 v66, 0x37800000, v65
	v_cndmask_b32_e32 v65, v65, v66, vcc
	v_cmp_class_f32_e32 vcc, v64, v177
	s_nop 1
	v_cndmask_b32_e32 v64, v65, v64, vcc
	v_div_scale_f32 v65, s[0:1], v64, v64, 1.0
	v_rcp_f32_e32 v66, v65
	v_div_scale_f32 v67, vcc, 1.0, v64, 1.0
	s_lshl_b64 s[0:1], s[70:71], 11
	v_fma_f32 v68, -v65, v66, 1.0
	v_fmac_f32_e32 v66, v68, v66
	v_mul_f32_e32 v68, v67, v66
	v_fma_f32 v69, -v65, v68, v67
	v_fmac_f32_e32 v68, v69, v66
	v_fma_f32 v65, -v65, v68, v67
	v_div_fmas_f32 v65, v65, v66, v68
	v_div_fixup_f32 v64, v65, v64, 1.0
	v_pk_mul_f32 v[60:61], v[60:61], v[64:65] op_sel_hi:[1,0]
	v_pk_mul_f32 v[62:63], v[62:63], v[64:65] op_sel_hi:[1,0]
	v_pk_fma_f32 v[60:61], v[82:83], v[60:61], v[0:1]
	v_pk_fma_f32 v[62:63], v[80:81], v[62:63], v[2:3]
	v_bfe_u32 v65, v60, 16, 1
	v_add3_u32 v65, v60, v65, s59
	v_bfe_u32 v66, v61, 16, 1
	v_lshrrev_b32_e32 v65, 16, v65
	v_add3_u32 v66, v61, v66, s59
	v_and_or_b32 v68, v66, s60, v65
	v_bfe_u32 v65, v62, 16, 1
	v_add3_u32 v65, v62, v65, s59
	v_bfe_u32 v66, v63, 16, 1
	v_lshrrev_b32_e32 v65, 16, v65
	v_add3_u32 v66, v63, v66, s59
	v_and_or_b32 v69, v66, s60, v65
	v_cndmask_b32_e64 v65, 0, 1, s[68:69]
	v_lshl_add_u64 v[66:67], v[98:99], 0, s[0:1]
	v_cmp_ne_u32_e64 s[0:1], 1, v65
	s_andn2_b64 vcc, exec, s[68:69]
	v_lshl_add_u64 v[136:137], v[66:67], 0, v[128:129]
	global_store_dwordx2 v[136:137], v[68:69], off
	s_cbranch_vccnz .LBB0_174
	v_lshl_add_u64 v[136:137], v[96:97], 0, v[120:121]
	global_store_dwordx4 v[136:137], v[60:63], off
; __device__ __forceinline__ unsigned pk2(float lo, float hi) { return f2bf(lo) | (f2bf(hi) << 16); }
; __device__ __forceinline__ void norm_mod_phase(const float* x, const float* x0src, size_t x0stride, float* h0buf, const float* g, const float* sh, const float* sc, bf16* XN, int gw, int NGW, int lane) {
;     ...
;         for (int r = 0; r < 4; ++r) { const int t = wi + wpb * (k + r); const bool t0 = t == 0; const size_t row = (size_t)b * T + t;
;             float ss = 0.f;
; #pragma unroll
;             for (int j = 0; j < 4; ++j) ss += (v[r][j].x * v[r][j].x + v[r][j].y * v[r][j].y) + (v[r][j].z * v[r][j].z + v[r][j].w * v[r][j].w);
;             const float rstd = 1.f / sqrtf(wave_sum(ss) * (1.f / D) + EPS);
; #pragma unroll
;             for (int j = 0; j < 4; ++j) { const int col = 4 * lane + 256 * j;
;                 const f32x4 h = v[r][j] * rstd * gm[j] + s0[j];
;                 v2u o; o.x = pk2(h.x, h.y); o.y = pk2(h.z, h.w);
;                 *(v2u*)(XN + row * D + col) = o;
;                 if (t0) *(f32x4*)(h0buf + b * D + col) = h; } }
.LBB0_174:
	v_mov_b32_e32 v65, v64
	v_pk_mul_f32 v[56:57], v[56:57], v[64:65]
	v_mov_b32_e32 v60, v64
	v_pk_fma_f32 v[56:57], v[86:87], v[56:57], v[4:5]
	v_mov_b32_e32 v61, v64
	v_bfe_u32 v62, v56, 16, 1
	v_pk_mul_f32 v[58:59], v[58:59], v[60:61]
	v_add3_u32 v62, v56, v62, s59
	v_bfe_u32 v63, v57, 16, 1
	v_pk_fma_f32 v[58:59], v[84:85], v[58:59], v[6:7]
	v_lshrrev_b32_e32 v62, 16, v62
	v_add3_u32 v63, v57, v63, s59
	v_and_or_b32 v62, v63, s60, v62
	v_bfe_u32 v63, v58, 16, 1
	v_add3_u32 v63, v58, v63, s59
	v_bfe_u32 v68, v59, 16, 1
	v_lshrrev_b32_e32 v63, 16, v63
	v_add3_u32 v68, v59, v68, s59
	v_and_or_b32 v63, v68, s60, v63
	s_and_b64 vcc, exec, s[0:1]
	v_lshl_add_u64 v[136:137], v[66:67], 0, v[130:131]
	global_store_dwordx2 v[136:137], v[62:63], off
	s_cbranch_vccnz .LBB0_176
	v_lshl_add_u64 v[136:137], v[96:97], 0, v[122:123]
	global_store_dwordx4 v[136:137], v[56:59], off
.LBB0_176:
	v_pk_mul_f32 v[52:53], v[52:53], v[64:65]
	v_pk_mul_f32 v[54:55], v[54:55], v[60:61]
	v_pk_fma_f32 v[52:53], v[90:91], v[52:53], v[8:9]
	v_pk_fma_f32 v[54:55], v[88:89], v[54:55], v[10:11]
	v_bfe_u32 v56, v52, 16, 1
	v_add3_u32 v56, v52, v56, s59
	v_bfe_u32 v57, v53, 16, 1
	v_lshrrev_b32_e32 v56, 16, v56
	v_add3_u32 v57, v53, v57, s59
	v_and_or_b32 v56, v57, s60, v56
	v_bfe_u32 v57, v54, 16, 1
	v_add3_u32 v57, v54, v57, s59
	v_bfe_u32 v58, v55, 16, 1
	v_lshrrev_b32_e32 v57, 16, v57
	v_add3_u32 v58, v55, v58, s59
	v_and_or_b32 v57, v58, s60, v57
	s_and_b64 vcc, exec, s[0:1]
	v_lshl_add_u64 v[136:137], v[66:67], 0, v[132:133]
	global_store_dwordx2 v[136:137], v[56:57], off
	s_cbranch_vccnz .LBB0_178
	v_lshl_add_u64 v[136:137], v[96:97], 0, v[124:125]
	global_store_dwordx4 v[136:137], v[52:55], off
.LBB0_178:
	v_pk_mul_f32 v[48:49], v[48:49], v[64:65]
	s_nop 0
	v_mov_b32_e32 v52, v64
	v_mov_b32_e32 v53, v64
	v_pk_fma_f32 v[48:49], v[94:95], v[48:49], v[12:13]
	v_pk_mul_f32 v[50:51], v[50:51], v[52:53]
	v_bfe_u32 v52, v48, 16, 1
	v_add3_u32 v52, v48, v52, s59
	v_bfe_u32 v53, v49, 16, 1
	v_pk_fma_f32 v[50:51], v[92:93], v[50:51], v[14:15]
	v_lshrrev_b32_e32 v52, 16, v52
	v_add3_u32 v53, v49, v53, s59
	v_and_or_b32 v52, v53, s60, v52
	v_bfe_u32 v53, v50, 16, 1
	v_add3_u32 v53, v50, v53, s59
	v_bfe_u32 v54, v51, 16, 1
	v_lshrrev_b32_e32 v53, 16, v53
	v_add3_u32 v54, v51, v54, s59
	v_and_or_b32 v53, v54, s60, v53
	s_and_b64 vcc, exec, s[0:1]
	v_lshl_add_u64 v[136:137], v[66:67], 0, v[134:135]
	global_store_dwordx2 v[136:137], v[52:53], off
	s_cbranch_vccnz .LBB0_180
	v_lshl_add_u64 v[136:137], v[96:97], 0, v[126:127]
	global_store_dwordx4 v[136:137], v[48:51], off
.LBB0_180:
	s_waitcnt vmcnt(15)
	s_nop 0
	v_pk_mul_f32 v[48:49], v[46:47], v[46:47]
	v_pk_mul_f32 v[50:51], v[44:45], v[44:45]
	s_nop 0
	v_pk_mov_b32 v[52:53], v[50:51], v[48:49] op_sel:[1,0]
	v_mov_b32_e32 v51, v49
	v_pk_add_f32 v[48:49], v[52:53], v[50:51]
	s_waitcnt vmcnt(14)
	v_pk_mul_f32 v[50:51], v[42:43], v[42:43]
	v_pk_mul_f32 v[52:53], v[40:41], v[40:41]
	v_pk_add_f32 v[48:49], v[48:49], v[48:49] op_sel:[0,1] op_sel_hi:[1,0]
	v_pk_mov_b32 v[54:55], v[52:53], v[50:51] op_sel:[1,0]
	v_mov_b32_e32 v53, v51
	v_pk_add_f32 v[50:51], v[54:55], v[52:53]
	s_waitcnt vmcnt(12)
	v_mul_f32_e32 v52, v32, v32
	v_mul_f32_e32 v53, v33, v33
	v_pk_add_f32 v[50:51], v[50:51], v[50:51] op_sel:[0,1] op_sel_hi:[1,0]
	v_mov_b32_e32 v49, v52
	v_mov_b32_e32 v51, v53
	v_pk_add_f32 v[48:49], v[48:49], v[50:51]
	v_mul_f32_e32 v50, v37, v37
	v_mul_f32_e32 v52, v39, v39
	v_mul_f32_e32 v54, v34, v34
	v_mul_f32_e32 v55, v35, v35
	v_pk_fma_f32 v[50:51], v[36:37], v[36:37], v[50:51] op_sel_hi:[1,1,0]
	v_pk_fma_f32 v[52:53], v[38:39], v[38:39], v[52:53] op_sel_hi:[1,1,0]
	v_mov_b32_e32 v51, v54
	v_mov_b32_e32 v53, v55
	v_pk_add_f32 v[50:51], v[50:51], v[52:53]
	s_nop 0
	v_pk_add_f32 v[48:49], v[48:49], v[50:51]
	s_nop 0
	v_add_f32_e32 v48, v48, v49
	ds_bpermute_b32 v49, v104, v48
	s_waitcnt lgkmcnt(0)
	v_add_f32_e32 v48, v48, v49
	ds_bpermute_b32 v49, v105, v48
	s_waitcnt lgkmcnt(0)
	v_add_f32_e32 v48, v48, v49
	ds_bpermute_b32 v49, v106, v48
	s_waitcnt lgkmcnt(0)
	v_add_f32_e32 v48, v48, v49
	ds_bpermute_b32 v49, v107, v48
	s_waitcnt lgkmcnt(0)
	v_add_f32_e32 v48, v48, v49
	ds_bpermute_b32 v49, v108, v48
	s_waitcnt lgkmcnt(0)
	v_add_f32_e32 v48, v48, v49
	ds_bpermute_b32 v49, v109, v48
	s_waitcnt lgkmcnt(0)
	v_add_f32_e32 v48, v48, v49
	v_fmamk_f32 v48, v48, 0x3a800000, v161
	v_mul_f32_e32 v49, 0x4f800000, v48
	v_cmp_gt_f32_e32 vcc, s58, v48
	s_nop 1
	v_cndmask_b32_e32 v48, v48, v49, vcc
	v_sqrt_f32_e32 v49, v48
	s_nop 0
	v_add_u32_e32 v50, -1, v49
	v_add_u32_e32 v51, 1, v49
	v_fma_f32 v52, -v50, v49, v48
	v_fma_f32 v53, -v51, v49, v48
	v_cmp_ge_f32_e64 s[0:1], 0, v52
	s_nop 1
	v_cndmask_b32_e64 v49, v49, v50, s[0:1]
	v_cmp_lt_f32_e64 s[0:1], 0, v53
	s_nop 1
	v_cndmask_b32_e64 v49, v49, v51, s[0:1]
	v_mul_f32_e32 v50, 0x37800000, v49
	v_cndmask_b32_e32 v49, v49, v50, vcc
	v_cmp_class_f32_e32 vcc, v48, v177
	s_nop 1
	v_cndmask_b32_e32 v48, v49, v48, vcc
	v_div_scale_f32 v49, s[0:1], v48, v48, 1.0
	v_rcp_f32_e32 v50, v49
	v_div_scale_f32 v51, vcc, 1.0, v48, 1.0
	s_lshl_b64 s[0:1], s[66:67], 11
	v_fma_f32 v52, -v49, v50, 1.0
	v_fmac_f32_e32 v50, v52, v50
	v_mul_f32_e32 v52, v51, v50
	v_fma_f32 v53, -v49, v52, v51
	v_fmac_f32_e32 v52, v53, v50
	v_fma_f32 v49, -v49, v52, v51
	v_div_fmas_f32 v49, v49, v50, v52
	v_div_fixup_f32 v48, v49, v48, 1.0
	v_pk_mul_f32 v[44:45], v[44:45], v[48:49] op_sel_hi:[1,0]
	v_pk_mul_f32 v[46:47], v[46:47], v[48:49] op_sel_hi:[1,0]
	v_pk_fma_f32 v[44:45], v[82:83], v[44:45], v[0:1]
	v_pk_fma_f32 v[46:47], v[80:81], v[46:47], v[2:3]
	v_bfe_u32 v49, v44, 16, 1
	v_add3_u32 v49, v44, v49, s59
	v_bfe_u32 v50, v45, 16, 1
	v_lshrrev_b32_e32 v49, 16, v49
	v_add3_u32 v50, v45, v50, s59
	v_and_or_b32 v52, v50, s60, v49
	v_bfe_u32 v49, v46, 16, 1
	v_add3_u32 v49, v46, v49, s59
	v_bfe_u32 v50, v47, 16, 1
	v_lshrrev_b32_e32 v49, 16, v49
	v_add3_u32 v50, v47, v50, s59
	v_and_or_b32 v53, v50, s60, v49
	v_cndmask_b32_e64 v49, 0, 1, s[64:65]
	v_lshl_add_u64 v[50:51], v[98:99], 0, s[0:1]
	v_cmp_ne_u32_e64 s[0:1], 1, v49
	s_andn2_b64 vcc, exec, s[64:65]
	v_lshl_add_u64 v[136:137], v[50:51], 0, v[128:129]
	global_store_dwordx2 v[136:137], v[52:53], off
	s_cbranch_vccnz .LBB0_182
	v_lshl_add_u64 v[136:137], v[96:97], 0, v[120:121]
	global_store_dwordx4 v[136:137], v[44:47], off
; __device__ __forceinline__ unsigned pk2(float lo, float hi) { return f2bf(lo) | (f2bf(hi) << 16); }
; __device__ __forceinline__ void norm_mod_phase(const float* x, const float* x0src, size_t x0stride, float* h0buf, const float* g, const float* sh, const float* sc, bf16* XN, int gw, int NGW, int lane) {
;     ...
;         for (int r = 0; r < 4; ++r) { const int t = wi + wpb * (k + r); const bool t0 = t == 0; const size_t row = (size_t)b * T + t;
;             float ss = 0.f;
; #pragma unroll
;             for (int j = 0; j < 4; ++j) ss += (v[r][j].x * v[r][j].x + v[r][j].y * v[r][j].y) + (v[r][j].z * v[r][j].z + v[r][j].w * v[r][j].w);
;             const float rstd = 1.f / sqrtf(wave_sum(ss) * (1.f / D) + EPS);
; #pragma unroll
;             for (int j = 0; j < 4; ++j) { const int col = 4 * lane + 256 * j;
;                 const f32x4 h = v[r][j] * rstd * gm[j] + s0[j];
;                 v2u o; o.x = pk2(h.x, h.y); o.y = pk2(h.z, h.w);
;                 *(v2u*)(XN + row * D + col) = o;
;                 if (t0) *(f32x4*)(h0buf + b * D + col) = h; } }
.LBB0_182:
	v_mov_b32_e32 v49, v48
	v_pk_mul_f32 v[40:41], v[40:41], v[48:49]
	v_mov_b32_e32 v44, v48
	v_pk_fma_f32 v[40:41], v[86:87], v[40:41], v[4:5]
	v_mov_b32_e32 v45, v48
	v_bfe_u32 v46, v40, 16, 1
	v_pk_mul_f32 v[42:43], v[42:43], v[44:45]
	v_add3_u32 v46, v40, v46, s59
	v_bfe_u32 v47, v41, 16, 1
	v_pk_fma_f32 v[42:43], v[84:85], v[42:43], v[6:7]
	v_lshrrev_b32_e32 v46, 16, v46
	v_add3_u32 v47, v41, v47, s59
	v_and_or_b32 v46, v47, s60, v46
	v_bfe_u32 v47, v42, 16, 1
	v_add3_u32 v47, v42, v47, s59
	v_bfe_u32 v52, v43, 16, 1
	v_lshrrev_b32_e32 v47, 16, v47
	v_add3_u32 v52, v43, v52, s59
	v_and_or_b32 v47, v52, s60, v47
	s_and_b64 vcc, exec, s[0:1]
	v_lshl_add_u64 v[136:137], v[50:51], 0, v[130:131]
	global_store_dwordx2 v[136:137], v[46:47], off
	s_cbranch_vccnz .LBB0_184
	v_lshl_add_u64 v[136:137], v[96:97], 0, v[122:123]
	global_store_dwordx4 v[136:137], v[40:43], off
.LBB0_184:
	v_pk_mul_f32 v[36:37], v[36:37], v[48:49]
	v_pk_mul_f32 v[38:39], v[38:39], v[44:45]
	v_pk_fma_f32 v[36:37], v[90:91], v[36:37], v[8:9]
	v_pk_fma_f32 v[38:39], v[88:89], v[38:39], v[10:11]
	v_bfe_u32 v40, v36, 16, 1
	v_add3_u32 v40, v36, v40, s59
	v_bfe_u32 v41, v37, 16, 1
	v_lshrrev_b32_e32 v40, 16, v40
	v_add3_u32 v41, v37, v41, s59
	v_and_or_b32 v40, v41, s60, v40
	v_bfe_u32 v41, v38, 16, 1
	v_add3_u32 v41, v38, v41, s59
	v_bfe_u32 v42, v39, 16, 1
	v_lshrrev_b32_e32 v41, 16, v41
	v_add3_u32 v42, v39, v42, s59
	v_and_or_b32 v41, v42, s60, v41
	s_and_b64 vcc, exec, s[0:1]
	v_lshl_add_u64 v[136:137], v[50:51], 0, v[132:133]
	global_store_dwordx2 v[136:137], v[40:41], off
	s_cbranch_vccnz .LBB0_186
	v_lshl_add_u64 v[136:137], v[96:97], 0, v[124:125]
	global_store_dwordx4 v[136:137], v[36:39], off
.LBB0_186:
	v_pk_mul_f32 v[32:33], v[32:33], v[48:49]
	s_nop 0
	v_mov_b32_e32 v36, v48
	v_mov_b32_e32 v37, v48
	v_pk_fma_f32 v[32:33], v[94:95], v[32:33], v[12:13]
	v_pk_mul_f32 v[34:35], v[34:35], v[36:37]
	v_bfe_u32 v36, v32, 16, 1
	v_add3_u32 v36, v32, v36, s59
	v_bfe_u32 v37, v33, 16, 1
	v_pk_fma_f32 v[34:35], v[92:93], v[34:35], v[14:15]
	v_lshrrev_b32_e32 v36, 16, v36
	v_add3_u32 v37, v33, v37, s59
	v_and_or_b32 v36, v37, s60, v36
	v_bfe_u32 v37, v34, 16, 1
	v_add3_u32 v37, v34, v37, s59
	v_bfe_u32 v38, v35, 16, 1
	v_lshrrev_b32_e32 v37, 16, v37
	v_add3_u32 v38, v35, v38, s59
	v_and_or_b32 v37, v38, s60, v37
	s_and_b64 vcc, exec, s[0:1]
	v_lshl_add_u64 v[136:137], v[50:51], 0, v[134:135]
	global_store_dwordx2 v[136:137], v[36:37], off
	s_cbranch_vccnz .LBB0_188
	v_lshl_add_u64 v[136:137], v[96:97], 0, v[126:127]
	global_store_dwordx4 v[136:137], v[32:35], off
.LBB0_188:
	s_waitcnt vmcnt(15)
	s_nop 0
	v_pk_mul_f32 v[32:33], v[30:31], v[30:31]
	v_pk_mul_f32 v[34:35], v[28:29], v[28:29]
	s_nop 0
	v_pk_mov_b32 v[36:37], v[34:35], v[32:33] op_sel:[1,0]
	v_mov_b32_e32 v35, v33
	v_pk_add_f32 v[32:33], v[36:37], v[34:35]
	s_waitcnt vmcnt(14)
	v_pk_mul_f32 v[34:35], v[26:27], v[26:27]
	v_pk_mul_f32 v[36:37], v[24:25], v[24:25]
	v_pk_add_f32 v[32:33], v[32:33], v[32:33] op_sel:[0,1] op_sel_hi:[1,0]
	v_pk_mov_b32 v[38:39], v[36:37], v[34:35] op_sel:[1,0]
	v_mov_b32_e32 v37, v35
	v_pk_add_f32 v[34:35], v[38:39], v[36:37]
	s_waitcnt vmcnt(12)
	v_mul_f32_e32 v36, v16, v16
	v_mul_f32_e32 v37, v17, v17
	v_pk_add_f32 v[34:35], v[34:35], v[34:35] op_sel:[0,1] op_sel_hi:[1,0]
	v_mov_b32_e32 v33, v36
	v_mov_b32_e32 v35, v37
	v_pk_add_f32 v[32:33], v[32:33], v[34:35]
	v_mul_f32_e32 v34, v21, v21
	v_mul_f32_e32 v36, v23, v23
	v_mul_f32_e32 v38, v18, v18
	v_mul_f32_e32 v39, v19, v19
	v_pk_fma_f32 v[34:35], v[20:21], v[20:21], v[34:35] op_sel_hi:[1,1,0]
	v_pk_fma_f32 v[36:37], v[22:23], v[22:23], v[36:37] op_sel_hi:[1,1,0]
	v_mov_b32_e32 v35, v38
	v_mov_b32_e32 v37, v39
	v_pk_add_f32 v[34:35], v[34:35], v[36:37]
	s_nop 0
	v_pk_add_f32 v[32:33], v[32:33], v[34:35]
	s_nop 0
	v_add_f32_e32 v32, v32, v33
	ds_bpermute_b32 v33, v104, v32
	s_waitcnt lgkmcnt(0)
	v_add_f32_e32 v32, v32, v33
	ds_bpermute_b32 v33, v105, v32
	s_waitcnt lgkmcnt(0)
	v_add_f32_e32 v32, v32, v33
	ds_bpermute_b32 v33, v106, v32
	s_waitcnt lgkmcnt(0)
	v_add_f32_e32 v32, v32, v33
	ds_bpermute_b32 v33, v107, v32
	s_waitcnt lgkmcnt(0)
	v_add_f32_e32 v32, v32, v33
	ds_bpermute_b32 v33, v108, v32
	s_waitcnt lgkmcnt(0)
	v_add_f32_e32 v32, v32, v33
	ds_bpermute_b32 v33, v109, v32
	s_waitcnt lgkmcnt(0)
	v_add_f32_e32 v32, v32, v33
	v_fmamk_f32 v32, v32, 0x3a800000, v161
	v_mul_f32_e32 v33, 0x4f800000, v32
	v_cmp_gt_f32_e32 vcc, s58, v32
	s_nop 1
	v_cndmask_b32_e32 v32, v32, v33, vcc
	v_sqrt_f32_e32 v33, v32
	s_nop 0
	v_add_u32_e32 v34, -1, v33
	v_add_u32_e32 v35, 1, v33
	v_fma_f32 v36, -v34, v33, v32
	v_fma_f32 v37, -v35, v33, v32
	v_cmp_ge_f32_e64 s[0:1], 0, v36
	s_nop 1
	v_cndmask_b32_e64 v33, v33, v34, s[0:1]
	v_cmp_lt_f32_e64 s[0:1], 0, v37
	s_nop 1
	v_cndmask_b32_e64 v33, v33, v35, s[0:1]
	v_mul_f32_e32 v34, 0x37800000, v33
	v_cndmask_b32_e32 v33, v33, v34, vcc
	v_cmp_class_f32_e32 vcc, v32, v177
	s_nop 1
	v_cndmask_b32_e32 v32, v33, v32, vcc
	v_div_scale_f32 v33, s[0:1], v32, v32, 1.0
	v_rcp_f32_e32 v34, v33
	v_div_scale_f32 v35, vcc, 1.0, v32, 1.0
	s_lshl_b64 s[0:1], s[6:7], 11
	v_fma_f32 v36, -v33, v34, 1.0
	v_fmac_f32_e32 v34, v36, v34
	v_mul_f32_e32 v36, v35, v34
	v_fma_f32 v37, -v33, v36, v35
	v_fmac_f32_e32 v36, v37, v34
	v_fma_f32 v33, -v33, v36, v35
	v_div_fmas_f32 v33, v33, v34, v36
	v_div_fixup_f32 v32, v33, v32, 1.0
	v_pk_mul_f32 v[28:29], v[28:29], v[32:33] op_sel_hi:[1,0]
	v_pk_mul_f32 v[30:31], v[30:31], v[32:33] op_sel_hi:[1,0]
	v_pk_fma_f32 v[28:29], v[82:83], v[28:29], v[0:1]
	v_pk_fma_f32 v[30:31], v[80:81], v[30:31], v[2:3]
	v_bfe_u32 v33, v28, 16, 1
	v_add3_u32 v33, v28, v33, s59
	v_bfe_u32 v34, v29, 16, 1
	v_lshrrev_b32_e32 v33, 16, v33
	v_add3_u32 v34, v29, v34, s59
	v_and_or_b32 v36, v34, s60, v33
	v_bfe_u32 v33, v30, 16, 1
	v_add3_u32 v33, v30, v33, s59
	v_bfe_u32 v34, v31, 16, 1
	v_lshrrev_b32_e32 v33, 16, v33
	v_add3_u32 v34, v31, v34, s59
	v_and_or_b32 v37, v34, s60, v33
	v_cndmask_b32_e64 v33, 0, 1, s[4:5]
	v_lshl_add_u64 v[34:35], v[98:99], 0, s[0:1]
	v_cmp_ne_u32_e64 s[0:1], 1, v33
	s_andn2_b64 vcc, exec, s[4:5]
	v_lshl_add_u64 v[136:137], v[34:35], 0, v[128:129]
	global_store_dwordx2 v[136:137], v[36:37], off
	s_cbranch_vccnz .LBB0_190
	v_lshl_add_u64 v[136:137], v[96:97], 0, v[120:121]
	global_store_dwordx4 v[136:137], v[28:31], off
; __device__ __forceinline__ unsigned pk2(float lo, float hi) { return f2bf(lo) | (f2bf(hi) << 16); }
; __device__ __forceinline__ void norm_mod_phase(const float* x, const float* x0src, size_t x0stride, float* h0buf, const float* g, const float* sh, const float* sc, bf16* XN, int gw, int NGW, int lane) {
;     ...
;         for (int r = 0; r < 4; ++r) { const int t = wi + wpb * (k + r); const bool t0 = t == 0; const size_t row = (size_t)b * T + t;
;             float ss = 0.f;
; #pragma unroll
;             for (int j = 0; j < 4; ++j) ss += (v[r][j].x * v[r][j].x + v[r][j].y * v[r][j].y) + (v[r][j].z * v[r][j].z + v[r][j].w * v[r][j].w);
;             const float rstd = 1.f / sqrtf(wave_sum(ss) * (1.f / D) + EPS);
; #pragma unroll
;             for (int j = 0; j < 4; ++j) { const int col = 4 * lane + 256 * j;
;                 const f32x4 h = v[r][j] * rstd * gm[j] + s0[j];
;                 v2u o; o.x = pk2(h.x, h.y); o.y = pk2(h.z, h.w);
;                 *(v2u*)(XN + row * D + col) = o;
;                 if (t0) *(f32x4*)(h0buf + b * D + col) = h; } }
.LBB0_190:
	v_mov_b32_e32 v33, v32
	v_pk_mul_f32 v[24:25], v[24:25], v[32:33]
	v_mov_b32_e32 v28, v32
	v_pk_fma_f32 v[24:25], v[86:87], v[24:25], v[4:5]
	v_mov_b32_e32 v29, v32
	v_bfe_u32 v30, v24, 16, 1
	v_pk_mul_f32 v[26:27], v[26:27], v[28:29]
	v_add3_u32 v30, v24, v30, s59
	v_bfe_u32 v31, v25, 16, 1
	v_pk_fma_f32 v[26:27], v[84:85], v[26:27], v[6:7]
	v_lshrrev_b32_e32 v30, 16, v30
	v_add3_u32 v31, v25, v31, s59
	v_and_or_b32 v30, v31, s60, v30
	v_bfe_u32 v31, v26, 16, 1
	v_add3_u32 v31, v26, v31, s59
	v_bfe_u32 v36, v27, 16, 1
	v_lshrrev_b32_e32 v31, 16, v31
	v_add3_u32 v36, v27, v36, s59
	v_and_or_b32 v31, v36, s60, v31
	s_and_b64 vcc, exec, s[0:1]
	v_lshl_add_u64 v[136:137], v[34:35], 0, v[130:131]
	global_store_dwordx2 v[136:137], v[30:31], off
	s_cbranch_vccnz .LBB0_192
	v_lshl_add_u64 v[136:137], v[96:97], 0, v[122:123]
	global_store_dwordx4 v[136:137], v[24:27], off
.LBB0_192:
	v_pk_mul_f32 v[20:21], v[20:21], v[32:33]
	v_pk_mul_f32 v[22:23], v[22:23], v[28:29]
	v_pk_fma_f32 v[20:21], v[90:91], v[20:21], v[8:9]
	v_pk_fma_f32 v[22:23], v[88:89], v[22:23], v[10:11]
	v_bfe_u32 v24, v20, 16, 1
	v_add3_u32 v24, v20, v24, s59
	v_bfe_u32 v25, v21, 16, 1
	v_lshrrev_b32_e32 v24, 16, v24
	v_add3_u32 v25, v21, v25, s59
	v_and_or_b32 v24, v25, s60, v24
	v_bfe_u32 v25, v22, 16, 1
	v_add3_u32 v25, v22, v25, s59
	v_bfe_u32 v26, v23, 16, 1
	v_lshrrev_b32_e32 v25, 16, v25
	v_add3_u32 v26, v23, v26, s59
	v_and_or_b32 v25, v26, s60, v25
	s_and_b64 vcc, exec, s[0:1]
	v_lshl_add_u64 v[136:137], v[34:35], 0, v[132:133]
	global_store_dwordx2 v[136:137], v[24:25], off
	s_cbranch_vccnz .LBB0_194
	v_lshl_add_u64 v[136:137], v[96:97], 0, v[124:125]
	global_store_dwordx4 v[136:137], v[20:23], off
.LBB0_194:
	v_pk_mul_f32 v[16:17], v[16:17], v[32:33]
	s_nop 0
	v_mov_b32_e32 v20, v32
	v_mov_b32_e32 v21, v32
	v_pk_fma_f32 v[16:17], v[94:95], v[16:17], v[12:13]
	v_pk_mul_f32 v[18:19], v[18:19], v[20:21]
	v_bfe_u32 v20, v16, 16, 1
	v_add3_u32 v20, v16, v20, s59
	v_bfe_u32 v21, v17, 16, 1
	v_pk_fma_f32 v[18:19], v[92:93], v[18:19], v[14:15]
	v_lshrrev_b32_e32 v20, 16, v20
	v_add3_u32 v21, v17, v21, s59
	v_and_or_b32 v20, v21, s60, v20
	v_bfe_u32 v21, v18, 16, 1
	v_add3_u32 v21, v18, v21, s59
	v_bfe_u32 v22, v19, 16, 1
	v_lshrrev_b32_e32 v21, 16, v21
	v_add3_u32 v22, v19, v22, s59
	v_and_or_b32 v21, v22, s60, v21
	s_and_b64 vcc, exec, s[0:1]
	v_lshl_add_u64 v[136:137], v[34:35], 0, v[134:135]
	global_store_dwordx2 v[136:137], v[20:21], off
	s_cbranch_vccnz .LBB0_163
	v_lshl_add_u64 v[136:137], v[96:97], 0, v[126:127]
	global_store_dwordx4 v[136:137], v[16:19], off
	s_branch .LBB0_163

; __device__ __forceinline__ void norm_mod_phase(const float* x, const float* x0src, size_t x0stride, float* h0buf, const float* g, const float* sh, const float* sc, bf16* XN, int gw, int NGW, int lane) {
;     const int wpb = NGW / BATCH, rpw = T / wpb;
;     const int b = gw / wpb, wi = gw - b * wpb;
.LBB0_1138:
	s_cmp_le_i32 s28, s8
	s_cselect_b64 s[2:3], -1, 0
	s_and_b64 s[0:1], s[2:3], s[0:1]
	s_andn2_b64 vcc, exec, s[0:1]
	s_cbranch_vccnz .LBB0_1174
	s_mov_b32 s4, s30
	s_mov_b32 s1, s10
	v_readlane_b32 s0, v255, 0
	v_readlane_b32 s3, v255, 11
	v_mov_b32_e32 v0, v160
	v_mov_b32_e32 v1, s0
	s_abs_i32 s0, s4
	v_mov_b32_e32 v6, s3
	ds_read2_b64 v[2:5], v1 offset1:1
	ds_read_b64 v[6:7], v6
	v_cvt_f32_u32_e32 v1, s0
	s_sub_i32 s7, 0, s0
	s_ashr_i32 s18, s4, 31
	v_readfirstlane_b32 s2, v0
	v_rcp_iflag_f32_e32 v1, v1
	s_waitcnt lgkmcnt(0)
	v_readfirstlane_b32 s5, v4
	v_readfirstlane_b32 s6, v5
	v_readfirstlane_b32 s16, v2
	v_mul_f32_e32 v1, 0x4f7ffffe, v1
	v_cvt_u32_f32_e32 v1, v1
	v_readfirstlane_b32 s17, v3
	v_readfirstlane_b32 s3, v6
	v_readfirstlane_b32 s20, v7
	v_readfirstlane_b32 s19, v1
	s_mul_i32 s7, s7, s19
	s_mul_hi_u32 s7, s19, s7
	s_add_i32 s19, s19, s7
	s_lshr_b32 s7, s19, 20
	s_mul_i32 s8, s7, s0
	s_sub_i32 s8, 0x1000, s8
	s_add_i32 s9, s7, 1
	s_sub_i32 s12, s8, s0
	s_cmp_ge_u32 s8, s0
	s_cselect_b32 s7, s9, s7
	s_cselect_b32 s8, s12, s8
	s_add_i32 s9, s7, 1
	s_cmp_ge_u32 s8, s0
	s_cselect_b32 s7, s9, s7
	s_xor_b32 s7, s7, s18
	s_sub_i32 s8, s7, s18
	s_cmp_lt_i32 s8, 1
	s_cbranch_scc1 .LBB0_1174
; __device__ __forceinline__ void norm_mod_phase(const float* x, const float* x0src, size_t x0stride, float* h0buf, const float* g, const float* sh, const float* sc, bf16* XN, int gw, int NGW, int lane) {
;     const int wpb = NGW / BATCH, rpw = T / wpb;
;     const int b = gw / wpb, wi = gw - b * wpb;
;     f32x4 gm[4], s0[4];
; #pragma unroll
;     for (int j = 0; j < 4; ++j) { const int col = 4 * lane + 256 * j; gm[j] = *(const f32x4*)(g + col) * (*(const f32x4*)(sc + b * NMOD + col) + 1.f); s0[j] = *(const f32x4*)(sh + b * NMOD + col); }
	s_mul_i32 s12, s62, 0xc000
	s_ashr_i32 s7, s2, 6
	s_lshl_b32 s9, s1, 3
	s_lshl_b32 s64, s62, 10
	s_add_i32 s1, s7, s9
	s_lshl_b64 s[66:67], s[12:13], 2
	s_mov_b32 s65, s13
	s_add_u32 s12, s5, s66
	s_addc_u32 s34, s6, s67
	s_lshl_b64 s[64:65], s[64:65], 2
	s_add_u32 s2, s3, s64
	s_addc_u32 s3, s20, s65
	s_ashr_i32 s20, s1, 31
	s_abs_i32 s1, s1
	s_mul_hi_u32 s19, s1, s19
	s_xor_b32 s18, s20, s18
	s_mul_i32 s20, s19, s0
	s_sub_i32 s1, s1, s20
	s_add_i32 s20, s19, 1
	s_sub_i32 s35, s1, s0
	s_cmp_ge_u32 s1, s0
	s_cselect_b32 s19, s20, s19
	s_cselect_b32 s1, s35, s1
	s_add_i32 s20, s19, 1
	s_cmp_ge_u32 s1, s0
	s_cselect_b32 s0, s20, s19
	s_xor_b32 s63, s0, s18
	s_sub_i32 s0, s63, s18
	s_mul_i32 s64, s0, 0x1800
	s_ashr_i32 s65, s64, 31
	s_lshl_b64 s[64:65], s[64:65], 2
	v_and_b32_e32 v16, 63, v0
	s_add_u32 s64, s12, s64
	s_addc_u32 s65, s34, s65
	v_lshlrev_b32_e32 v162, 4, v16
	v_readfirstlane_b32 s98, v160
	s_nop 3
	s_lshr_b32 s98, s98, 6
	v_and_b32_e32 v136, 63, v160
	v_lshlrev_b32_e32 v136, 4, v136
	s_add_i32 s99, s98, 0
	s_and_b32 s99, s99, 3
	s_lshl_b32 s99, s99, 10
	v_add_u32_e32 v116, s99, v136
	v_mov_b32_e32 v120, s99
	v_mov_b32_e32 v121, 0
	s_lshr_b32 s99, s99, 1
	v_mov_b32_e32 v128, s99
	v_mov_b32_e32 v129, 0
	s_add_i32 s99, s98, 1
	s_and_b32 s99, s99, 3
	s_lshl_b32 s99, s99, 10
	v_add_u32_e32 v117, s99, v136
	v_mov_b32_e32 v122, s99
	v_mov_b32_e32 v123, 0
	s_lshr_b32 s99, s99, 1
	v_mov_b32_e32 v130, s99
	v_mov_b32_e32 v131, 0
	s_add_i32 s99, s98, 2
	s_and_b32 s99, s99, 3
	s_lshl_b32 s99, s99, 10
	v_add_u32_e32 v118, s99, v136
	v_mov_b32_e32 v124, s99
	v_mov_b32_e32 v125, 0
	s_lshr_b32 s99, s99, 1
	v_mov_b32_e32 v132, s99
	v_mov_b32_e32 v133, 0
	s_add_i32 s99, s98, 3
	s_and_b32 s99, s99, 3
	s_lshl_b32 s99, s99, 10
	v_add_u32_e32 v119, s99, v136
	v_mov_b32_e32 v126, s99
	v_mov_b32_e32 v127, 0
	s_lshr_b32 s99, s99, 1
	v_mov_b32_e32 v134, s99
	v_mov_b32_e32 v135, 0
	v_lshl_add_u64 v[8:9], s[64:65], 0, v[162:163]
	s_movk_i32 s1, 0x4000
	v_add_co_u32_e32 v4, vcc, s1, v8
	global_load_dwordx4 v[0:3], v116, s[2:3]
	s_nop 0
	v_addc_co_u32_e32 v5, vcc, 0, v9, vcc
	v_lshl_add_u64 v[136:137], v[4:5], 0, v[120:121]
	global_load_dwordx4 v[4:7], v[136:137], off
	s_movk_i32 s1, 0x3000
	s_mov_b64 s[64:65], 0x4000
	v_lshl_add_u64 v[18:19], v[8:9], 0, s[64:65]
	s_mov_b64 s[64:65], 0x3000
	v_lshl_add_u64 v[22:23], v[8:9], 0, s[64:65]
	s_mul_i32 s19, s0, s4
	s_mov_b32 s12, 0
	v_lshlrev_b32_e32 v110, 4, v16
	s_waitcnt vmcnt(0)
	v_pk_add_f32 v[4:5], v[4:5], 1.0 op_sel_hi:[1,0]
	s_nop 0
	v_pk_mul_f32 v[82:83], v[0:1], v[4:5]
	v_add_co_u32_e32 v0, vcc, s1, v8
	v_pk_add_f32 v[6:7], v[6:7], 1.0 op_sel_hi:[1,0]
	s_nop 0
	v_addc_co_u32_e32 v1, vcc, 0, v9, vcc
	v_pk_mul_f32 v[80:81], v[2:3], v[6:7]
	v_lshl_add_u64 v[136:137], v[0:1], 0, v[120:121]
	global_load_dwordx4 v[0:3], v[136:137], off
	s_nop 0
	global_load_dwordx4 v[4:7], v117, s[2:3]
	v_lshl_add_u64 v[136:137], v[18:19], 0, v[122:123]
	global_load_dwordx4 v[8:11], v[136:137], off
	s_ashr_i32 s1, s0, 31
	v_cmp_lt_i32_e32 vcc, v228, v222
	s_waitcnt vmcnt(0)
	v_pk_add_f32 v[10:11], v[10:11], 1.0 op_sel_hi:[1,0]
	v_pk_add_f32 v[8:9], v[8:9], 1.0 op_sel_hi:[1,0]
	v_pk_mul_f32 v[84:85], v[6:7], v[10:11]
	v_pk_mul_f32 v[86:87], v[4:5], v[8:9]
	v_lshl_add_u64 v[136:137], v[22:23], 0, v[122:123]
	global_load_dwordx4 v[4:7], v[136:137], off
	global_load_dwordx4 v[8:11], v118, s[2:3]
	v_lshl_add_u64 v[136:137], v[18:19], 0, v[124:125]
	global_load_dwordx4 v[12:15], v[136:137], off
	v_cndmask_b32_e32 v17, v221, v228, vcc
	v_lshlrev_b32_e32 v104, 2, v17
	v_xor_b32_e32 v17, 2, v221
	v_cmp_lt_i32_e32 vcc, v17, v222
	s_waitcnt vmcnt(0)
	v_pk_add_f32 v[14:15], v[14:15], 1.0 op_sel_hi:[1,0]
	v_pk_add_f32 v[12:13], v[12:13], 1.0 op_sel_hi:[1,0]
	v_pk_mul_f32 v[88:89], v[10:11], v[14:15]
	v_pk_mul_f32 v[90:91], v[8:9], v[12:13]
	v_lshl_add_u64 v[136:137], v[22:23], 0, v[124:125]
	global_load_dwordx4 v[8:11], v[136:137], off
	global_load_dwordx4 v[12:15], v119, s[2:3]
	s_nop 0
	v_lshl_add_u64 v[136:137], v[18:19], 0, v[126:127]
	global_load_dwordx4 v[18:21], v[136:137], off
	s_lshl_b64 s[2:3], s[0:1], 24
	s_add_u32 s16, s16, s2
	s_addc_u32 s17, s17, s3
	s_lshl_b64 s[2:3], s[0:1], 12
	s_add_u32 s2, s5, s2
	s_addc_u32 s3, s6, s3
	s_add_u32 s20, s2, 0x590000
	s_addc_u32 s61, s3, 0
	s_lshl_b64 s[2:3], s[0:1], 23
	s_add_u32 s2, s5, s2
	s_addc_u32 s3, s6, s3
	s_lshl_b32 s0, s0, 10
	s_ashr_i32 s1, s0, 31
	s_lshl_b64 s[0:1], s[0:1], 2
	s_add_u32 s0, s5, s0
	s_addc_u32 s1, s6, s1
	v_cndmask_b32_e32 v17, v221, v17, vcc
	v_cmp_lt_i32_e32 vcc, v218, v222
	v_lshlrev_b32_e32 v105, 2, v17
	s_sub_i32 s76, s7, s19
	v_cndmask_b32_e32 v17, v221, v218, vcc
	v_cmp_lt_i32_e32 vcc, v219, v222
	v_lshlrev_b32_e32 v106, 2, v17
	s_waitcnt vmcnt(0)
	v_pk_add_f32 v[20:21], v[20:21], 1.0 op_sel_hi:[1,0]
	v_pk_add_f32 v[18:19], v[18:19], 1.0 op_sel_hi:[1,0]
	v_pk_mul_f32 v[92:93], v[14:15], v[20:21]
	v_pk_mul_f32 v[94:95], v[12:13], v[18:19]
	v_lshl_add_u64 v[136:137], v[22:23], 0, v[126:127]
	global_load_dwordx4 v[12:15], v[136:137], off
	v_lshl_add_u64 v[18:19], s[0:1], 0, v[162:163]
	s_mov_b64 s[0:1], 0x598000
	v_lshlrev_b32_e32 v162, 3, v16
	v_lshl_add_u64 v[96:97], v[18:19], 0, s[0:1]
	v_lshl_add_u64 v[18:19], s[2:3], 0, v[162:163]
	s_mov_b64 s[0:1], 0x6e00000
	v_lshl_add_u64 v[98:99], v[18:19], 0, s[0:1]
	s_sub_i32 s0, s18, s63
	s_add_i32 s1, s0, 1
	v_cndmask_b32_e32 v17, v221, v219, vcc
	v_cmp_lt_i32_e32 vcc, v254, v222
	s_mul_i32 s1, s4, s1
	v_lshlrev_b32_e32 v107, 2, v17
	v_cndmask_b32_e32 v17, v221, v254, vcc
	v_cmp_lt_i32_e32 vcc, v223, v222
	s_add_i32 s18, s7, s1
	s_add_i32 s1, s0, 2
	s_add_i32 s0, s0, 3
	v_lshlrev_b32_e32 v108, 2, v17
	v_cndmask_b32_e32 v17, v221, v223, vcc
	s_lshl_b32 s63, s4, 2
	s_mul_i32 s1, s4, s1
	s_mul_i32 s4, s4, s0
	v_lshlrev_b32_e32 v109, 2, v17
	s_add_i32 s74, s7, s1
	s_add_i32 s75, s7, s4
	s_branch .LBB0_1142

; __device__ __forceinline__ unsigned pk2(float lo, float hi) { return f2bf(lo) | (f2bf(hi) << 16); }
; __device__ __forceinline__ void norm_mod_phase(const float* x, const float* x0src, size_t x0stride, float* h0buf, const float* g, const float* sh, const float* sc, bf16* XN, int gw, int NGW, int lane) {
;     ...
;     for (int k = 0; k < rpw; k += 4) {
;         f32x4 v[4][4];
; #pragma unroll
;         for (int r = 0; r < 4; ++r) { const int t = wi + wpb * (k + r); const bool t0 = t == 0;
;             const f32x4* xr = (const f32x4*)(t0 ? x0src + (size_t)b * x0stride : x + ((size_t)b * T + t) * D) + lane;
; #pragma unroll
;             for (int j = 0; j < 4; ++j) v[r][j] = xr[64 * j]; }
;         __builtin_amdgcn_sched_barrier(0);
; #pragma unroll
;         for (int r = 0; r < 4; ++r) { const int t = wi + wpb * (k + r); const bool t0 = t == 0; const size_t row = (size_t)b * T + t;
;             float ss = 0.f;
; #pragma unroll
;             for (int j = 0; j < 4; ++j) ss += (v[r][j].x * v[r][j].x + v[r][j].y * v[r][j].y) + (v[r][j].z * v[r][j].z + v[r][j].w * v[r][j].w);
;             const float rstd = 1.f / sqrtf(wave_sum(ss) * (1.f / D) + EPS);
; #pragma unroll
;             for (int j = 0; j < 4; ++j) { const int col = 4 * lane + 256 * j;
;                 const f32x4 h = v[r][j] * rstd * gm[j] + s0[j];
;                 v2u o; o.x = pk2(h.x, h.y); o.y = pk2(h.z, h.w);
;                 *(v2u*)(XN + row * D + col) = o;
;                 if (t0) *(f32x4*)(h0buf + b * D + col) = h; } }
.LBB0_1142:
	s_add_i32 s0, s9, s76
	s_ashr_i32 s1, s0, 31
	s_lshl_b64 s[2:3], s[0:1], 12
	s_add_u32 s4, s16, s2
	s_addc_u32 s5, s17, s3
	s_cmp_eq_u32 s0, 0
	s_cselect_b64 s[70:71], -1, 0
	s_and_b64 s[2:3], s[70:71], exec
	s_cselect_b32 s72, s20, s4
	s_cselect_b32 s73, s61, s5
	s_add_i32 s68, s9, s18
	s_ashr_i32 s69, s68, 31
	s_lshl_b64 s[2:3], s[68:69], 12
	s_add_u32 s4, s16, s2
	s_addc_u32 s5, s17, s3
	s_cmp_eq_u32 s68, 0
	s_cselect_b64 s[66:67], -1, 0
	s_and_b64 s[2:3], s[66:67], exec
	s_cselect_b32 s78, s20, s4
	s_cselect_b32 s79, s61, s5
	s_add_i32 s64, s9, s74
	s_ashr_i32 s65, s64, 31
	s_lshl_b64 s[2:3], s[64:65], 12
	s_add_u32 s4, s16, s2
	s_addc_u32 s5, s17, s3
	s_cmp_eq_u32 s64, 0
	s_cselect_b64 s[6:7], -1, 0
	s_and_b64 s[2:3], s[6:7], exec
	s_cselect_b32 s80, s20, s4
	s_cselect_b32 s81, s61, s5
	s_add_i32 s4, s9, s75
	s_ashr_i32 s5, s4, 31
	s_lshl_b64 s[2:3], s[4:5], 12
	s_add_u32 s19, s16, s2
	s_addc_u32 s34, s17, s3
	s_cmp_eq_u32 s4, 0
	s_cselect_b64 s[2:3], -1, 0
	s_and_b64 s[82:83], s[2:3], exec
	s_cselect_b32 s82, s20, s19
	s_cselect_b32 s83, s61, s34
	global_load_dwordx4 v[76:79], v116, s[72:73]
	global_load_dwordx4 v[72:75], v117, s[72:73]
	global_load_dwordx4 v[68:71], v118, s[72:73]
	global_load_dwordx4 v[64:67], v119, s[72:73]
	global_load_dwordx4 v[60:63], v116, s[78:79]
	global_load_dwordx4 v[56:59], v117, s[78:79]
	global_load_dwordx4 v[52:55], v118, s[78:79]
	global_load_dwordx4 v[48:51], v119, s[78:79]
	global_load_dwordx4 v[44:47], v116, s[80:81]
	global_load_dwordx4 v[40:43], v117, s[80:81]
	global_load_dwordx4 v[36:39], v118, s[80:81]
	global_load_dwordx4 v[32:35], v119, s[80:81]
	global_load_dwordx4 v[28:31], v116, s[82:83]
	global_load_dwordx4 v[24:27], v117, s[82:83]
	global_load_dwordx4 v[20:23], v118, s[82:83]
	global_load_dwordx4 v[16:19], v119, s[82:83]
	s_lshl_b64 s[72:73], s[0:1], 11
	s_cmp_lg_u32 s0, 0
	s_waitcnt vmcnt(15)
	v_pk_mul_f32 v[100:101], v[78:79], v[78:79]
	v_pk_mul_f32 v[102:103], v[76:77], v[76:77]
	s_waitcnt vmcnt(12)
	v_mul_f32_e32 v111, v64, v64
	v_pk_mov_b32 v[112:113], v[102:103], v[100:101] op_sel:[1,0]
	v_mov_b32_e32 v103, v101
	v_pk_add_f32 v[100:101], v[112:113], v[102:103]
	v_pk_mul_f32 v[102:103], v[74:75], v[74:75]
	v_pk_mul_f32 v[112:113], v[72:73], v[72:73]
	v_pk_add_f32 v[100:101], v[100:101], v[100:101] op_sel:[0,1] op_sel_hi:[1,0]
	v_pk_mov_b32 v[114:115], v[112:113], v[102:103] op_sel:[1,0]
	v_mov_b32_e32 v113, v103
	v_pk_add_f32 v[102:103], v[114:115], v[112:113]
	v_mul_f32_e32 v112, v65, v65
	v_pk_add_f32 v[102:103], v[102:103], v[102:103] op_sel:[0,1] op_sel_hi:[1,0]
	v_mov_b32_e32 v101, v111
	v_mov_b32_e32 v103, v112
	v_pk_add_f32 v[100:101], v[100:101], v[102:103]
	v_mul_f32_e32 v102, v69, v69
	v_mul_f32_e32 v113, v66, v66
	v_pk_fma_f32 v[102:103], v[68:69], v[68:69], v[102:103] op_sel_hi:[1,1,0]
	v_mul_f32_e32 v112, v71, v71
	v_mul_f32_e32 v114, v67, v67
	v_mov_b32_e32 v103, v113
	v_pk_fma_f32 v[112:113], v[70:71], v[70:71], v[112:113] op_sel_hi:[1,1,0]
	s_nop 0
	v_mov_b32_e32 v113, v114
	v_pk_add_f32 v[102:103], v[102:103], v[112:113]
	s_nop 0
	v_pk_add_f32 v[100:101], v[100:101], v[102:103]
	s_nop 0
	v_add_f32_e32 v100, v100, v101
	ds_bpermute_b32 v101, v104, v100
	s_waitcnt lgkmcnt(0)
	v_add_f32_e32 v100, v100, v101
	ds_bpermute_b32 v101, v105, v100
	s_waitcnt lgkmcnt(0)
	v_add_f32_e32 v100, v100, v101
	ds_bpermute_b32 v101, v106, v100
	s_waitcnt lgkmcnt(0)
	v_add_f32_e32 v100, v100, v101
	ds_bpermute_b32 v101, v107, v100
	s_waitcnt lgkmcnt(0)
	v_add_f32_e32 v100, v100, v101
	ds_bpermute_b32 v101, v108, v100
	s_waitcnt lgkmcnt(0)
	v_add_f32_e32 v100, v100, v101
	ds_bpermute_b32 v101, v109, v100
	s_waitcnt lgkmcnt(0)
	v_add_f32_e32 v100, v100, v101
	v_fmamk_f32 v100, v100, 0x3a800000, v161
	v_mul_f32_e32 v101, 0x4f800000, v100
	v_cmp_gt_f32_e32 vcc, s58, v100
	s_nop 1
	v_cndmask_b32_e32 v100, v100, v101, vcc
	v_sqrt_f32_e32 v101, v100
	s_nop 0
	v_add_u32_e32 v102, -1, v101
	v_add_u32_e32 v103, 1, v101
	v_fma_f32 v111, -v102, v101, v100
	v_fma_f32 v112, -v103, v101, v100
	v_cmp_ge_f32_e64 s[0:1], 0, v111
	s_nop 1
	v_cndmask_b32_e64 v101, v101, v102, s[0:1]
	v_cmp_lt_f32_e64 s[0:1], 0, v112
	s_nop 1
	v_cndmask_b32_e64 v101, v101, v103, s[0:1]
	v_mul_f32_e32 v102, 0x37800000, v101
	v_cndmask_b32_e32 v101, v101, v102, vcc
	v_cmp_class_f32_e32 vcc, v100, v177
	s_nop 1
	v_cndmask_b32_e32 v100, v101, v100, vcc
	v_div_scale_f32 v101, s[0:1], v100, v100, 1.0
	v_rcp_f32_e32 v102, v101
	v_div_scale_f32 v103, vcc, 1.0, v100, 1.0
	v_fma_f32 v111, -v101, v102, 1.0
	v_fmac_f32_e32 v102, v111, v102
	v_mul_f32_e32 v111, v103, v102
	v_fma_f32 v112, -v101, v111, v103
	v_fmac_f32_e32 v111, v112, v102
	v_fma_f32 v101, -v101, v111, v103
	v_div_fmas_f32 v101, v101, v102, v111
	v_div_fixup_f32 v100, v101, v100, 1.0
	v_pk_mul_f32 v[76:77], v[76:77], v[100:101] op_sel_hi:[1,0]
	v_pk_mul_f32 v[78:79], v[78:79], v[100:101] op_sel_hi:[1,0]
	v_pk_fma_f32 v[76:77], v[82:83], v[76:77], v[0:1]
	v_pk_fma_f32 v[78:79], v[80:81], v[78:79], v[2:3]
	v_bfe_u32 v101, v76, 16, 1
	v_add3_u32 v101, v76, v101, s59
	v_bfe_u32 v102, v77, 16, 1
	v_lshrrev_b32_e32 v101, 16, v101
	v_add3_u32 v102, v77, v102, s59
	v_and_or_b32 v112, v102, s60, v101
	v_bfe_u32 v101, v78, 16, 1
	v_add3_u32 v101, v78, v101, s59
	v_bfe_u32 v102, v79, 16, 1
	v_lshrrev_b32_e32 v101, 16, v101
	v_add3_u32 v102, v79, v102, s59
	v_and_or_b32 v113, v102, s60, v101
	v_lshl_add_u64 v[102:103], v[98:99], 0, s[72:73]
	v_lshl_add_u64 v[136:137], v[102:103], 0, v[128:129]
	global_store_dwordx2 v[136:137], v[112:113], off
	s_cbranch_scc1 .LBB0_1144
	v_lshl_add_u64 v[136:137], v[96:97], 0, v[120:121]
	global_store_dwordx4 v[136:137], v[76:79], off
.LBB0_1144:
	v_mov_b32_e32 v101, v100
	v_pk_mul_f32 v[72:73], v[72:73], v[100:101]
	v_mov_b32_e32 v76, v100
	v_pk_fma_f32 v[72:73], v[86:87], v[72:73], v[4:5]
	v_mov_b32_e32 v77, v100
	v_bfe_u32 v78, v72, 16, 1
	v_pk_mul_f32 v[74:75], v[74:75], v[76:77]
	v_add3_u32 v78, v72, v78, s59
	v_bfe_u32 v79, v73, 16, 1
	v_pk_fma_f32 v[74:75], v[84:85], v[74:75], v[6:7]
	v_lshrrev_b32_e32 v78, 16, v78
	v_add3_u32 v79, v73, v79, s59
	v_and_or_b32 v78, v79, s60, v78
	v_bfe_u32 v79, v74, 16, 1
	v_add3_u32 v79, v74, v79, s59
	v_bfe_u32 v111, v75, 16, 1
	v_lshrrev_b32_e32 v79, 16, v79
	v_add3_u32 v111, v75, v111, s59
	v_and_or_b32 v79, v111, s60, v79
	v_cndmask_b32_e64 v111, 0, 1, s[70:71]
	v_cmp_ne_u32_e64 s[0:1], 1, v111
	s_andn2_b64 vcc, exec, s[70:71]
	v_lshl_add_u64 v[136:137], v[102:103], 0, v[130:131]
	global_store_dwordx2 v[136:137], v[78:79], off
	s_cbranch_vccnz .LBB0_1146
	v_lshl_add_u64 v[136:137], v[96:97], 0, v[122:123]
	global_store_dwordx4 v[136:137], v[72:75], off

; __device__ __forceinline__ unsigned pk2(float lo, float hi) { return f2bf(lo) | (f2bf(hi) << 16); }
; __device__ __forceinline__ void norm_mod_phase(const float* x, const float* x0src, size_t x0stride, float* h0buf, const float* g, const float* sh, const float* sc, bf16* XN, int gw, int NGW, int lane) {
;     ...
;         for (int r = 0; r < 4; ++r) { const int t = wi + wpb * (k + r); const bool t0 = t == 0; const size_t row = (size_t)b * T + t;
;             float ss = 0.f;
; #pragma unroll
;             for (int j = 0; j < 4; ++j) ss += (v[r][j].x * v[r][j].x + v[r][j].y * v[r][j].y) + (v[r][j].z * v[r][j].z + v[r][j].w * v[r][j].w);
;             const float rstd = 1.f / sqrtf(wave_sum(ss) * (1.f / D) + EPS);
; #pragma unroll
;             for (int j = 0; j < 4; ++j) { const int col = 4 * lane + 256 * j;
;                 const f32x4 h = v[r][j] * rstd * gm[j] + s0[j];
;                 v2u o; o.x = pk2(h.x, h.y); o.y = pk2(h.z, h.w);
;                 *(v2u*)(XN + row * D + col) = o;
;                 if (t0) *(f32x4*)(h0buf + b * D + col) = h; } }
.LBB0_1150:
	s_waitcnt vmcnt(15)
	s_nop 0
	v_pk_mul_f32 v[64:65], v[62:63], v[62:63]
	v_pk_mul_f32 v[66:67], v[60:61], v[60:61]
	s_nop 0
	v_pk_mov_b32 v[68:69], v[66:67], v[64:65] op_sel:[1,0]
	v_mov_b32_e32 v67, v65
	v_pk_add_f32 v[64:65], v[68:69], v[66:67]
	s_waitcnt vmcnt(14)
	v_pk_mul_f32 v[66:67], v[58:59], v[58:59]
	v_pk_mul_f32 v[68:69], v[56:57], v[56:57]
	v_pk_add_f32 v[64:65], v[64:65], v[64:65] op_sel:[0,1] op_sel_hi:[1,0]
	v_pk_mov_b32 v[70:71], v[68:69], v[66:67] op_sel:[1,0]
	v_mov_b32_e32 v69, v67
	v_pk_add_f32 v[66:67], v[70:71], v[68:69]
	s_waitcnt vmcnt(12)
	v_mul_f32_e32 v68, v48, v48
	v_mul_f32_e32 v69, v49, v49
	v_pk_add_f32 v[66:67], v[66:67], v[66:67] op_sel:[0,1] op_sel_hi:[1,0]
	v_mov_b32_e32 v65, v68
	v_mov_b32_e32 v67, v69
	v_pk_add_f32 v[64:65], v[64:65], v[66:67]
	v_mul_f32_e32 v66, v53, v53
	v_mul_f32_e32 v68, v55, v55
	v_mul_f32_e32 v70, v50, v50
	v_mul_f32_e32 v71, v51, v51
	v_pk_fma_f32 v[66:67], v[52:53], v[52:53], v[66:67] op_sel_hi:[1,1,0]
	v_pk_fma_f32 v[68:69], v[54:55], v[54:55], v[68:69] op_sel_hi:[1,1,0]
	v_mov_b32_e32 v67, v70
	v_mov_b32_e32 v69, v71
	v_pk_add_f32 v[66:67], v[66:67], v[68:69]
	s_nop 0
	v_pk_add_f32 v[64:65], v[64:65], v[66:67]
	s_nop 0
	v_add_f32_e32 v64, v64, v65
	ds_bpermute_b32 v65, v104, v64
	s_waitcnt lgkmcnt(0)
	v_add_f32_e32 v64, v64, v65
	ds_bpermute_b32 v65, v105, v64
	s_waitcnt lgkmcnt(0)
	v_add_f32_e32 v64, v64, v65
	ds_bpermute_b32 v65, v106, v64
	s_waitcnt lgkmcnt(0)
	v_add_f32_e32 v64, v64, v65
	ds_bpermute_b32 v65, v107, v64
	s_waitcnt lgkmcnt(0)
	v_add_f32_e32 v64, v64, v65
	ds_bpermute_b32 v65, v108, v64
	s_waitcnt lgkmcnt(0)
	v_add_f32_e32 v64, v64, v65
	ds_bpermute_b32 v65, v109, v64
	s_waitcnt lgkmcnt(0)
	v_add_f32_e32 v64, v64, v65
	v_fmamk_f32 v64, v64, 0x3a800000, v161
	v_mul_f32_e32 v65, 0x4f800000, v64
	v_cmp_gt_f32_e32 vcc, s58, v64
	s_nop 1
	v_cndmask_b32_e32 v64, v64, v65, vcc
	v_sqrt_f32_e32 v65, v64
	s_nop 0
	v_add_u32_e32 v66, -1, v65
	v_add_u32_e32 v67, 1, v65
	v_fma_f32 v68, -v66, v65, v64
	v_fma_f32 v69, -v67, v65, v64
	v_cmp_ge_f32_e64 s[0:1], 0, v68
	s_nop 1
	v_cndmask_b32_e64 v65, v65, v66, s[0:1]
	v_cmp_lt_f32_e64 s[0:1], 0, v69
	s_nop 1
	v_cndmask_b32_e64 v65, v65, v67, s[0:1]
	v_mul_f32_e32 v66, 0x37800000, v65
	v_cndmask_b32_e32 v65, v65, v66, vcc
	v_cmp_class_f32_e32 vcc, v64, v177
	s_nop 1
	v_cndmask_b32_e32 v64, v65, v64, vcc
	v_div_scale_f32 v65, s[0:1], v64, v64, 1.0
	v_rcp_f32_e32 v66, v65
	v_div_scale_f32 v67, vcc, 1.0, v64, 1.0
	s_lshl_b64 s[0:1], s[68:69], 11
	v_fma_f32 v68, -v65, v66, 1.0
	v_fmac_f32_e32 v66, v68, v66
	v_mul_f32_e32 v68, v67, v66
	v_fma_f32 v69, -v65, v68, v67
	v_fmac_f32_e32 v68, v69, v66
	v_fma_f32 v65, -v65, v68, v67
	v_div_fmas_f32 v65, v65, v66, v68
	v_div_fixup_f32 v64, v65, v64, 1.0
	v_pk_mul_f32 v[60:61], v[60:61], v[64:65] op_sel_hi:[1,0]
	v_pk_mul_f32 v[62:63], v[62:63], v[64:65] op_sel_hi:[1,0]
	v_pk_fma_f32 v[60:61], v[82:83], v[60:61], v[0:1]
	v_pk_fma_f32 v[62:63], v[80:81], v[62:63], v[2:3]
	v_bfe_u32 v65, v60, 16, 1
	v_add3_u32 v65, v60, v65, s59
	v_bfe_u32 v66, v61, 16, 1
	v_lshrrev_b32_e32 v65, 16, v65
	v_add3_u32 v66, v61, v66, s59
	v_and_or_b32 v68, v66, s60, v65
	v_bfe_u32 v65, v62, 16, 1
	v_add3_u32 v65, v62, v65, s59
	v_bfe_u32 v66, v63, 16, 1
	v_lshrrev_b32_e32 v65, 16, v65
	v_add3_u32 v66, v63, v66, s59
	v_and_or_b32 v69, v66, s60, v65
	v_cndmask_b32_e64 v65, 0, 1, s[66:67]
	v_lshl_add_u64 v[66:67], v[98:99], 0, s[0:1]
	v_cmp_ne_u32_e64 s[0:1], 1, v65
	s_andn2_b64 vcc, exec, s[66:67]
	v_lshl_add_u64 v[136:137], v[66:67], 0, v[128:129]
	global_store_dwordx2 v[136:137], v[68:69], off
	s_cbranch_vccnz .LBB0_1152
	v_lshl_add_u64 v[136:137], v[96:97], 0, v[120:121]
	global_store_dwordx4 v[136:137], v[60:63], off

; __device__ __forceinline__ unsigned pk2(float lo, float hi) { return f2bf(lo) | (f2bf(hi) << 16); }
; __device__ __forceinline__ void norm_mod_phase(const float* x, const float* x0src, size_t x0stride, float* h0buf, const float* g, const float* sh, const float* sc, bf16* XN, int gw, int NGW, int lane) {
;     ...
;         for (int r = 0; r < 4; ++r) { const int t = wi + wpb * (k + r); const bool t0 = t == 0; const size_t row = (size_t)b * T + t;
;             float ss = 0.f;
; #pragma unroll
;             for (int j = 0; j < 4; ++j) ss += (v[r][j].x * v[r][j].x + v[r][j].y * v[r][j].y) + (v[r][j].z * v[r][j].z + v[r][j].w * v[r][j].w);
;             const float rstd = 1.f / sqrtf(wave_sum(ss) * (1.f / D) + EPS);
; #pragma unroll
;             for (int j = 0; j < 4; ++j) { const int col = 4 * lane + 256 * j;
;                 const f32x4 h = v[r][j] * rstd * gm[j] + s0[j];
;                 v2u o; o.x = pk2(h.x, h.y); o.y = pk2(h.z, h.w);
;                 *(v2u*)(XN + row * D + col) = o;
;                 if (t0) *(f32x4*)(h0buf + b * D + col) = h; } }
.LBB0_1158:
	s_waitcnt vmcnt(15)
	s_nop 0
	v_pk_mul_f32 v[48:49], v[46:47], v[46:47]
	v_pk_mul_f32 v[50:51], v[44:45], v[44:45]
	s_nop 0
	v_pk_mov_b32 v[52:53], v[50:51], v[48:49] op_sel:[1,0]
	v_mov_b32_e32 v51, v49
	v_pk_add_f32 v[48:49], v[52:53], v[50:51]
	s_waitcnt vmcnt(14)
	v_pk_mul_f32 v[50:51], v[42:43], v[42:43]
	v_pk_mul_f32 v[52:53], v[40:41], v[40:41]
	v_pk_add_f32 v[48:49], v[48:49], v[48:49] op_sel:[0,1] op_sel_hi:[1,0]
	v_pk_mov_b32 v[54:55], v[52:53], v[50:51] op_sel:[1,0]
	v_mov_b32_e32 v53, v51
	v_pk_add_f32 v[50:51], v[54:55], v[52:53]
	s_waitcnt vmcnt(12)
	v_mul_f32_e32 v52, v32, v32
	v_mul_f32_e32 v53, v33, v33
	v_pk_add_f32 v[50:51], v[50:51], v[50:51] op_sel:[0,1] op_sel_hi:[1,0]
	v_mov_b32_e32 v49, v52
	v_mov_b32_e32 v51, v53
	v_pk_add_f32 v[48:49], v[48:49], v[50:51]
	v_mul_f32_e32 v50, v37, v37
	v_mul_f32_e32 v52, v39, v39
	v_mul_f32_e32 v54, v34, v34
	v_mul_f32_e32 v55, v35, v35
	v_pk_fma_f32 v[50:51], v[36:37], v[36:37], v[50:51] op_sel_hi:[1,1,0]
	v_pk_fma_f32 v[52:53], v[38:39], v[38:39], v[52:53] op_sel_hi:[1,1,0]
	v_mov_b32_e32 v51, v54
	v_mov_b32_e32 v53, v55
	v_pk_add_f32 v[50:51], v[50:51], v[52:53]
	s_nop 0
	v_pk_add_f32 v[48:49], v[48:49], v[50:51]
	s_nop 0
	v_add_f32_e32 v48, v48, v49
	ds_bpermute_b32 v49, v104, v48
	s_waitcnt lgkmcnt(0)
	v_add_f32_e32 v48, v48, v49
	ds_bpermute_b32 v49, v105, v48
	s_waitcnt lgkmcnt(0)
	v_add_f32_e32 v48, v48, v49
	ds_bpermute_b32 v49, v106, v48
	s_waitcnt lgkmcnt(0)
	v_add_f32_e32 v48, v48, v49
	ds_bpermute_b32 v49, v107, v48
	s_waitcnt lgkmcnt(0)
	v_add_f32_e32 v48, v48, v49
	ds_bpermute_b32 v49, v108, v48
	s_waitcnt lgkmcnt(0)
	v_add_f32_e32 v48, v48, v49
	ds_bpermute_b32 v49, v109, v48
	s_waitcnt lgkmcnt(0)
	v_add_f32_e32 v48, v48, v49
	v_fmamk_f32 v48, v48, 0x3a800000, v161
	v_mul_f32_e32 v49, 0x4f800000, v48
	v_cmp_gt_f32_e32 vcc, s58, v48
	s_nop 1
	v_cndmask_b32_e32 v48, v48, v49, vcc
	v_sqrt_f32_e32 v49, v48
	s_nop 0
	v_add_u32_e32 v50, -1, v49
	v_add_u32_e32 v51, 1, v49
	v_fma_f32 v52, -v50, v49, v48
	v_fma_f32 v53, -v51, v49, v48
	v_cmp_ge_f32_e64 s[0:1], 0, v52
	s_nop 1
	v_cndmask_b32_e64 v49, v49, v50, s[0:1]
	v_cmp_lt_f32_e64 s[0:1], 0, v53
	s_nop 1
	v_cndmask_b32_e64 v49, v49, v51, s[0:1]
	v_mul_f32_e32 v50, 0x37800000, v49
	v_cndmask_b32_e32 v49, v49, v50, vcc
	v_cmp_class_f32_e32 vcc, v48, v177
	s_nop 1
	v_cndmask_b32_e32 v48, v49, v48, vcc
	v_div_scale_f32 v49, s[0:1], v48, v48, 1.0
	v_rcp_f32_e32 v50, v49
	v_div_scale_f32 v51, vcc, 1.0, v48, 1.0
	s_lshl_b64 s[0:1], s[64:65], 11
	v_fma_f32 v52, -v49, v50, 1.0
	v_fmac_f32_e32 v50, v52, v50
	v_mul_f32_e32 v52, v51, v50
	v_fma_f32 v53, -v49, v52, v51
	v_fmac_f32_e32 v52, v53, v50
	v_fma_f32 v49, -v49, v52, v51
	v_div_fmas_f32 v49, v49, v50, v52
	v_div_fixup_f32 v48, v49, v48, 1.0
	v_pk_mul_f32 v[44:45], v[44:45], v[48:49] op_sel_hi:[1,0]
	v_pk_mul_f32 v[46:47], v[46:47], v[48:49] op_sel_hi:[1,0]
	v_pk_fma_f32 v[44:45], v[82:83], v[44:45], v[0:1]
	v_pk_fma_f32 v[46:47], v[80:81], v[46:47], v[2:3]
	v_bfe_u32 v49, v44, 16, 1
	v_add3_u32 v49, v44, v49, s59
	v_bfe_u32 v50, v45, 16, 1
	v_lshrrev_b32_e32 v49, 16, v49
	v_add3_u32 v50, v45, v50, s59
	v_and_or_b32 v52, v50, s60, v49
	v_bfe_u32 v49, v46, 16, 1
	v_add3_u32 v49, v46, v49, s59
	v_bfe_u32 v50, v47, 16, 1
	v_lshrrev_b32_e32 v49, 16, v49
	v_add3_u32 v50, v47, v50, s59
	v_and_or_b32 v53, v50, s60, v49
	v_cndmask_b32_e64 v49, 0, 1, s[6:7]
	v_lshl_add_u64 v[50:51], v[98:99], 0, s[0:1]
	v_cmp_ne_u32_e64 s[0:1], 1, v49
	s_andn2_b64 vcc, exec, s[6:7]
	v_lshl_add_u64 v[136:137], v[50:51], 0, v[128:129]
	global_store_dwordx2 v[136:137], v[52:53], off
	s_cbranch_vccnz .LBB0_1160
	v_lshl_add_u64 v[136:137], v[96:97], 0, v[120:121]
	global_store_dwordx4 v[136:137], v[44:47], off

; __device__ __forceinline__ unsigned pk2(float lo, float hi) { return f2bf(lo) | (f2bf(hi) << 16); }
; __device__ __forceinline__ void norm_mod_phase(const float* x, const float* x0src, size_t x0stride, float* h0buf, const float* g, const float* sh, const float* sc, bf16* XN, int gw, int NGW, int lane) {
;     ...
;         for (int r = 0; r < 4; ++r) { const int t = wi + wpb * (k + r); const bool t0 = t == 0; const size_t row = (size_t)b * T + t;
;             float ss = 0.f;
; #pragma unroll
;             for (int j = 0; j < 4; ++j) ss += (v[r][j].x * v[r][j].x + v[r][j].y * v[r][j].y) + (v[r][j].z * v[r][j].z + v[r][j].w * v[r][j].w);
;             const float rstd = 1.f / sqrtf(wave_sum(ss) * (1.f / D) + EPS);
; #pragma unroll
;             for (int j = 0; j < 4; ++j) { const int col = 4 * lane + 256 * j;
;                 const f32x4 h = v[r][j] * rstd * gm[j] + s0[j];
;                 v2u o; o.x = pk2(h.x, h.y); o.y = pk2(h.z, h.w);
;                 *(v2u*)(XN + row * D + col) = o;
;                 if (t0) *(f32x4*)(h0buf + b * D + col) = h; } }
.LBB0_1166:
	s_waitcnt vmcnt(15)
	s_nop 0
	v_pk_mul_f32 v[32:33], v[30:31], v[30:31]
	v_pk_mul_f32 v[34:35], v[28:29], v[28:29]
	s_nop 0
	v_pk_mov_b32 v[36:37], v[34:35], v[32:33] op_sel:[1,0]
	v_mov_b32_e32 v35, v33
	v_pk_add_f32 v[32:33], v[36:37], v[34:35]
	s_waitcnt vmcnt(14)
	v_pk_mul_f32 v[34:35], v[26:27], v[26:27]
	v_pk_mul_f32 v[36:37], v[24:25], v[24:25]
	v_pk_add_f32 v[32:33], v[32:33], v[32:33] op_sel:[0,1] op_sel_hi:[1,0]
	v_pk_mov_b32 v[38:39], v[36:37], v[34:35] op_sel:[1,0]
	v_mov_b32_e32 v37, v35
	v_pk_add_f32 v[34:35], v[38:39], v[36:37]
	s_waitcnt vmcnt(12)
	v_mul_f32_e32 v36, v16, v16
	v_mul_f32_e32 v37, v17, v17
	v_pk_add_f32 v[34:35], v[34:35], v[34:35] op_sel:[0,1] op_sel_hi:[1,0]
	v_mov_b32_e32 v33, v36
	v_mov_b32_e32 v35, v37
	v_pk_add_f32 v[32:33], v[32:33], v[34:35]
	v_mul_f32_e32 v34, v21, v21
	v_mul_f32_e32 v36, v23, v23
	v_mul_f32_e32 v38, v18, v18
	v_mul_f32_e32 v39, v19, v19
	v_pk_fma_f32 v[34:35], v[20:21], v[20:21], v[34:35] op_sel_hi:[1,1,0]
	v_pk_fma_f32 v[36:37], v[22:23], v[22:23], v[36:37] op_sel_hi:[1,1,0]
	v_mov_b32_e32 v35, v38
	v_mov_b32_e32 v37, v39
	v_pk_add_f32 v[34:35], v[34:35], v[36:37]
	s_nop 0
	v_pk_add_f32 v[32:33], v[32:33], v[34:35]
	s_nop 0
	v_add_f32_e32 v32, v32, v33
	ds_bpermute_b32 v33, v104, v32
	s_waitcnt lgkmcnt(0)
	v_add_f32_e32 v32, v32, v33
	ds_bpermute_b32 v33, v105, v32
	s_waitcnt lgkmcnt(0)
	v_add_f32_e32 v32, v32, v33
	ds_bpermute_b32 v33, v106, v32
	s_waitcnt lgkmcnt(0)
	v_add_f32_e32 v32, v32, v33
	ds_bpermute_b32 v33, v107, v32
	s_waitcnt lgkmcnt(0)
	v_add_f32_e32 v32, v32, v33
	ds_bpermute_b32 v33, v108, v32
	s_waitcnt lgkmcnt(0)
	v_add_f32_e32 v32, v32, v33
	ds_bpermute_b32 v33, v109, v32
	s_waitcnt lgkmcnt(0)
	v_add_f32_e32 v32, v32, v33
	v_fmamk_f32 v32, v32, 0x3a800000, v161
	v_mul_f32_e32 v33, 0x4f800000, v32
	v_cmp_gt_f32_e32 vcc, s58, v32
	s_nop 1
	v_cndmask_b32_e32 v32, v32, v33, vcc
	v_sqrt_f32_e32 v33, v32
	s_nop 0
	v_add_u32_e32 v34, -1, v33
	v_add_u32_e32 v35, 1, v33
	v_fma_f32 v36, -v34, v33, v32
	v_fma_f32 v37, -v35, v33, v32
	v_cmp_ge_f32_e64 s[0:1], 0, v36
	s_nop 1
	v_cndmask_b32_e64 v33, v33, v34, s[0:1]
	v_cmp_lt_f32_e64 s[0:1], 0, v37
	s_nop 1
	v_cndmask_b32_e64 v33, v33, v35, s[0:1]
	v_mul_f32_e32 v34, 0x37800000, v33
	v_cndmask_b32_e32 v33, v33, v34, vcc
	v_cmp_class_f32_e32 vcc, v32, v177
	s_nop 1
	v_cndmask_b32_e32 v32, v33, v32, vcc
	v_div_scale_f32 v33, s[0:1], v32, v32, 1.0
	v_rcp_f32_e32 v34, v33
	v_div_scale_f32 v35, vcc, 1.0, v32, 1.0
	s_lshl_b64 s[0:1], s[4:5], 11
	v_fma_f32 v36, -v33, v34, 1.0
	v_fmac_f32_e32 v34, v36, v34
	v_mul_f32_e32 v36, v35, v34
	v_fma_f32 v37, -v33, v36, v35
	v_fmac_f32_e32 v36, v37, v34
	v_fma_f32 v33, -v33, v36, v35
	v_div_fmas_f32 v33, v33, v34, v36
	v_div_fixup_f32 v32, v33, v32, 1.0
	v_pk_mul_f32 v[28:29], v[28:29], v[32:33] op_sel_hi:[1,0]
	v_pk_mul_f32 v[30:31], v[30:31], v[32:33] op_sel_hi:[1,0]
	v_pk_fma_f32 v[28:29], v[82:83], v[28:29], v[0:1]
	v_pk_fma_f32 v[30:31], v[80:81], v[30:31], v[2:3]
	v_bfe_u32 v33, v28, 16, 1
	v_add3_u32 v33, v28, v33, s59
	v_bfe_u32 v34, v29, 16, 1
	v_lshrrev_b32_e32 v33, 16, v33
	v_add3_u32 v34, v29, v34, s59
	v_and_or_b32 v36, v34, s60, v33
	v_bfe_u32 v33, v30, 16, 1
	v_add3_u32 v33, v30, v33, s59
	v_bfe_u32 v34, v31, 16, 1
	v_lshrrev_b32_e32 v33, 16, v33
	v_add3_u32 v34, v31, v34, s59
	v_and_or_b32 v37, v34, s60, v33
	v_cndmask_b32_e64 v33, 0, 1, s[2:3]
	v_lshl_add_u64 v[34:35], v[98:99], 0, s[0:1]
	v_cmp_ne_u32_e64 s[0:1], 1, v33
	s_andn2_b64 vcc, exec, s[2:3]
	v_lshl_add_u64 v[136:137], v[34:35], 0, v[128:129]
	global_store_dwordx2 v[136:137], v[36:37], off
	s_cbranch_vccnz .LBB0_1168
	v_lshl_add_u64 v[136:137], v[96:97], 0, v[120:121]
	global_store_dwordx4 v[136:137], v[28:31], off
